# 272-row units + post-tile 16-row strip mini-GEMM in P3,P4,P6 (removes 16-tile tail rounds)
# baseline (speedup 1.0000x reference)
; #define LAS __attribute__((address_space(3)))
;     __device__ bool next(int i, Unit& u) const {
;         const long L = (long)i * G + c; if (L >= nwg) return false;
;         int wgid = (int)L; { const int q = nwg / NXCD, r = nwg % NXCD, xcd = wgid % NXCD, off = wgid / NXCD; wgid = (xcd < r ? xcd * (q + 1) : r * (q + 1) + (xcd - r) * q) + off; }
;         const int nig = WGM * nN, gid = wgid / nig, fm = gid * WGM, gsz = (nM - fm) < WGM ? (nM - fm) : WGM;
;         u.pm = fm + ((wgid % nig) % gsz); u.pn = (wgid % nig) / gsz; return true;
;     }
; __device__ __forceinline__ unsigned cvt_pk_bf16(float lo, float hi) { unsigned r; asm volatile("v_cvt_pk_bf16_f32 %0, %1, %2" : "=v"(r) : "v"(lo), "v"(hi)); return r; }
; template <class Epi>
; __device__ __forceinline__ void gemm_phase(LAS unsigned char* lds, const Gemm g, const StaticOrder& S, const Epi& E) {
;     const int tid = threadIdx.x, wid = __builtin_amdgcn_readfirstlane(tid >> 6), lane = tid & 63, wr = wid >> 2, wc = wid & 3, fr = lane & 15, fq = lane >> 4;
;     const int K = g.K, nt = K / BK;
;     unsigned voffA[2], voffB[2];
; #pragma unroll
;     for (int i = 0; i < 2; ++i) { int R, C; stage_rc(tid * 16 + i * 8192, R, C); const int Rb = (R & ~31) + perm32(R & 31);
;         voffA[i] = (unsigned)(R * K + C) * 2u; voffB[i] = (unsigned)(Rb * K + C) * 2u; }
;     const size_t kstep = (size_t)(BK * 2);
;     const size_t hstep = (size_t)HALF * K * 2;
;     const size_t tstep = 2 * hstep;
;     const unsigned ldsw = (unsigned)wid * 1024u;
;     const int aoff = lds_byte(wr * 64 + fr, fq * 8), boff = lds_byte(wc * 32 + fr, fq * 8);
;     ...
;     Unit cur, nxt; int ui = 0;
;     if (!S.next(0, cur)) return;
;     f32x4 acc[2][2][4][2];
; #pragma unroll
;     for (int a = 0; a < 2; ++a)
; #pragma unroll
;         for (int b = 0; b < 2; ++b)
; #pragma unroll
;             for (int m = 0; m < 4; ++m)
; #pragma unroll
;                 for (int n = 0; n < 2; ++n) acc[a][b][m][n] = (f32x4){0.f, 0.f, 0.f, 0.f};
;     bf16x8 At[4][2], B0[2][2], B1[2][2];
;     const char* cA = (const char*)g.A + (size_t)cur.pm * tstep; const char* cB = (const char*)g.Bt + (size_t)cur.pn * tstep;
;     PG8_STAGE(PG8_SB(0, 0), cB, voffB); PG8_STAGE(PG8_SB(0, 1), cB + hstep, voffB); PG8_STAGE(PG8_SA(0, 0), cA, voffA); PG8_STAGE(PG8_SA(0, 1), cA + hstep, voffA);
;     if (wr == 1) PG8_BAR;
;     PG8_WAIT_V(2); PG8_BAR;
.LBB0_656:
	s_or_b64 exec, exec, s[0:1]
	s_cmp_lt_i32 s90, 4
	s_cselect_b64 s[0:1], -1, 0
	s_cmp_gt_i32 s91, 3
	s_cselect_b64 s[2:3], -1, 0
	s_and_b64 s[0:1], s[0:1], s[2:3]
	s_andn2_b64 vcc, exec, s[0:1]
	s_waitcnt lgkmcnt(0)
	s_barrier
	s_cbranch_vccnz .LBB0_675
	s_cmpk_gt_i32 s44, 0x10f
	v_readfirstlane_b32 s3, v134
	s_cbranch_scc1 .LBB0_675
	v_lshrrev_b32_e32 v0, 5, v134
	v_lshrrev_b32_e32 v2, 1, v134
	v_and_b32_e32 v0, 4, v0
	v_bfe_u32 v1, v134, 2, 2
	v_and_b32_e32 v11, 24, v2
	v_or3_b32 v0, v0, v1, v11
	v_lshlrev_b32_e32 v1, 4, v134
	v_add_u32_e32 v8, 0x2000, v1
	v_lshrrev_b32_e32 v2, 7, v8
	s_movk_i32 s0, 0xe0
	v_and_b32_e32 v4, 32, v134
	s_add_u32 s28, s88, 0x14000000
	v_and_or_b32 v3, v2, s0, v0
	v_bitop3_b32 v9, v1, v4, 48 bitop3:0x6c
	v_and_b32_e32 v10, 64, v134
	v_bfe_u32 v12, v134, 2, 4
	s_movk_i32 s0, 0xf0
	s_addc_u32 s29, s89, 0
	v_or_b32_e32 v1, v9, v10
	v_and_or_b32 v2, v2, s0, v12
	s_add_u32 s30, s88, 0x1600000
	v_lshl_or_b32 v138, v2, 12, v1
	v_lshrrev_b32_e32 v2, 3, v134
	s_movk_i32 s0, 0x60
	s_addc_u32 s31, s89, 0
	v_and_or_b32 v0, v2, s0, v0
	s_movk_i32 s0, 0x70
	s_ashr_i32 s34, s44, 31
	v_lshl_or_b32 v140, v0, 12, v1
	v_and_or_b32 v0, v2, s0, v12
	s_lshr_b32 s0, s34, 29
	s_add_i32 s0, s44, s0
	s_lshr_b32 s8, s3, 6
	s_ashr_i32 s1, s0, 3
	s_and_b32 s0, s0, -8
	s_lshr_b32 s10, s3, 8
	s_lshl_b32 s33, s8, 10
	s_sub_i32 s0, s44, s0
	s_cmp_lt_i32 s0, 0
	s_cselect_b32 s2, 35, 34
	s_mul_i32 s0, s0, s2
	s_add_i32 s0, s0, s1
	s_ashr_i32 s1, s0, 31
	s_lshr_b32 s1, s1, 27
	s_add_i32 s1, s0, s1
	s_ashr_i32 s1, s1, 5
	s_lshl_b32 s4, s1, 3
	s_sub_i32 s2, 0x44, s4
	s_lshl_b32 s1, s1, 5
	s_min_u32 s5, s2, 8
	s_sub_i32 s6, s0, s1
	v_lshl_or_b32 v136, v3, 12, v1
	s_sext_i32_i8 s0, s6
	v_cvt_f32_ubyte0_e32 v3, s5
	v_cvt_f32_i32_e32 v2, s0
	v_rcp_iflag_f32_e32 v4, v3
	v_lshl_or_b32 v142, v0, 12, v1
	s_ashr_i32 s0, s0, 30
	s_or_b32 s2, s0, 1
	v_mul_f32_e32 v0, v2, v4
	v_trunc_f32_e32 v0, v0
	v_fma_f32 v1, -v0, v3, v2
	v_cvt_i32_f32_e32 v0, v0
	v_cmp_ge_f32_e64 s[0:1], |v1|, v3
	s_and_b64 s[0:1], s[0:1], exec
	s_cselect_b32 s0, s2, 0
	v_readfirstlane_b32 s1, v0
	s_add_i32 s2, s1, s0
	s_mul_i32 s0, s2, s5
	s_sub_i32 s0, s6, s0
	s_sext_i32_i8 s0, s0
	s_add_i32 s24, s4, s0
	s_and_b32 s0, s44, 7
	s_lshr_b32 s1, s44, 3
	s_and_b32 s1, s1, 7
	s_lshl_b32 s0, s0, 3
	s_add_i32 s0, s0, s1
	s_mul_i32 s24, s0, 17
	s_lshr_b32 s2, s44, 6
	s_ashr_i32 s25, s24, 31
	s_bfe_i64 s[4:5], s[2:3], 0x80000
	s_lshl_b64 s[0:1], s[24:25], 16
	s_lshl_b64 s[4:5], s[4:5], 20
	s_add_u32 s22, s30, s4
	s_addc_u32 s23, s31, s5
	s_add_i32 s35, s33, 0
	s_add_i32 m0, s35, 0x10000
	v_mov_b32_e32 v141, 0
	global_load_lds_dwordx4 v140, s[22:23]
	s_add_i32 m0, s35, 0x12000
	s_add_u32 s4, s22, 0x80000
	global_load_lds_dwordx4 v136, s[22:23]
	s_addc_u32 s5, s23, 0
	s_add_i32 m0, s35, 0x14000
	v_mov_b32_e32 v137, v141
	global_load_lds_dwordx4 v140, s[4:5]
	s_add_i32 m0, s35, 0x16000
	s_add_u32 s20, s28, s0
	s_addc_u32 s21, s29, s1
	s_add_i32 s36, s35, 0x2000
	global_load_lds_dwordx4 v136, s[4:5]
	s_mov_b32 m0, s35
	s_add_u32 s0, s20, 0x80000
	global_load_lds_dwordx4 v142, s[20:21]
	s_mov_b32 m0, s36
	s_addc_u32 s1, s21, 0
	s_add_i32 s37, s35, 0x4000
	global_load_lds_dwordx4 v138, s[20:21]
	s_mov_b32 m0, s37
	s_add_i32 s38, s35, 0x6000
	global_load_lds_dwordx4 v142, s[0:1]
	s_mov_b32 m0, s38
	v_mov_b32_e32 v143, v141
	global_load_lds_dwordx4 v138, s[0:1]
	v_mov_b32_e32 v139, v141
	s_cmp_eq_u32 s10, 1
	s_mov_b32 s39, 0
	v_lshl_add_u64 v[6:7], s[22:23], 0, v[140:141]
	v_lshl_add_u64 v[4:5], s[22:23], 0, v[136:137]
	v_lshl_add_u64 v[0:1], s[20:21], 0, v[142:143]
	s_cselect_b64 s[0:1], -1, 0
	s_cmp_lg_u32 s10, 1
	v_lshl_add_u64 v[2:3], s[20:21], 0, v[138:139]
	s_cbranch_scc1 .LBB0_660
	s_barrier
.LBB0_660:
	s_add_u32 s4, s88, 0xfc00000
	s_addc_u32 s5, s89, 0
	s_add_u32 s6, s88, 0x3000000
	s_addc_u32 s7, s89, 0
	s_lshl_b32 s8, s8, 5
	s_and_b32 s14, s8, 0x60
	s_mov_b64 s[8:9], 0x80
	s_add_i32 m0, s35, 0x18000
	v_lshl_add_u64 v[6:7], v[6:7], 0, s[8:9]
	s_lshl_b32 s11, s10, 13
	s_lshl_b32 s15, s14, 7
	s_waitcnt vmcnt(2)
	s_barrier
	global_load_lds_dwordx4 v[6:7], off
	v_lshl_add_u64 v[4:5], v[4:5], 0, s[8:9]
	s_add_i32 m0, s35, 0x1a000
	s_add_i32 s40, s35, 0x8000
	s_add_i32 s41, s35, 0xa000
	global_load_lds_dwordx4 v[4:5], off
	v_lshl_add_u64 v[0:1], v[0:1], 0, s[8:9]
	s_mov_b32 m0, s40
	s_add_u32 s12, s22, 0x80080
	global_load_lds_dwordx4 v[0:1], off
	v_lshl_add_u64 v[0:1], v[2:3], 0, s[8:9]
	s_mov_b32 m0, s41
	s_addc_u32 s13, s23, 0
	global_load_lds_dwordx4 v[0:1], off
	s_add_i32 m0, s35, 0x1c000
	v_lshl_add_u64 v[0:1], s[12:13], 0, v[140:141]
	global_load_lds_dwordx4 v[0:1], off
	v_lshl_add_u64 v[0:1], s[12:13], 0, v[136:137]
	s_add_i32 m0, s35, 0x1e000
	v_lshlrev_b32_e32 v2, 2, v134
	global_load_lds_dwordx4 v[0:1], off
	v_and_b32_e32 v0, 15, v134
	v_lshlrev_b32_e32 v1, 1, v11
	v_lshl_or_b32 v133, s10, 6, v0
	v_lshl_or_b32 v0, v0, 6, v1
	v_and_b32_e32 v2, 32, v2
	s_sext_i32_i8 s25, s2
	v_bitop3_b32 v3, v0, s11, v2 bitop3:0xde
	v_lshlrev_b32_e32 v0, 6, v134
	s_movk_i32 s2, 0x3c0
	v_and_or_b32 v0, v0, s2, v1
	v_bitop3_b32 v135, s15, v0, v2 bitop3:0xf6
	v_lshlrev_b32_e32 v0, 9, v134
	v_and_b32_e32 v0, 0x70000, v0
	v_lshlrev_b32_e32 v2, 12, v12
	v_or3_b32 v0, v9, v0, v2
	s_mov_b64 s[12:13], 0x80080
	v_add_u32_e32 v0, v0, v10
	v_mov_b32_e32 v1, v141
	v_lshl_add_u64 v[144:145], v[0:1], 0, s[12:13]
	v_lshlrev_b32_e32 v0, 5, v8
	v_and_b32_e32 v0, 0xf0000, v0
	s_waitcnt vmcnt(6)
	v_or3_b32 v0, v9, v0, v2
	s_cmpk_lt_u32 s3, 0x100
	v_add_u32_e32 v0, v0, v10
	v_or_b32_e32 v176, 32, v133
	v_or_b32_e32 v177, 48, v133
	v_add_u32_e32 v178, 0x80, v133
	v_add_u32_e32 v179, 0x90, v133
	v_add_u32_e32 v180, 0xa0, v133
	v_add_u32_e32 v181, 0xb0, v133
	s_cselect_b64 s[10:11], -1, 0
	s_ashr_i32 s42, s94, 31
	s_mov_b32 s43, s94
	v_or_b32_e32 v182, s14, v11
	v_lshl_add_u64 v[146:147], v[0:1], 0, s[12:13]
	v_mov_b64_e32 v[148:149], 0x100
	v_mov_b64_e32 v[150:151], 0xff
	s_add_i32 s45, 0, 0x10000
	s_add_i32 s46, 0, 0x14000
	v_add_u32_e32 v183, 0, v3
	s_barrier
	s_branch .LBB0_663

; #define EPI_LOOP(...) _Pragma("unroll") for (int ai = 0; ai < 2; ++ai) _Pragma("unroll") for (int m = 0; m < 4; ++m) { const int row = u.pm * 256 + ai * 128 + wr * 64 + m * 16 + fr; \
;     _Pragma("unroll") for (int bj = 0; bj < 2; ++bj) { const int tc = bj * 128 + wc * 32 + 8 * fq; f32x4 v0 = acc[ai][bj][m][0], v1 = acc[ai][bj][m][1]; __VA_ARGS__ } }
; template <class Epi>
; __device__ __forceinline__ void gemm_phase(LAS unsigned char* lds, const Gemm g, const StaticOrder& S, const Epi& E) {
;     ...
;         const bool has_next = S.next(ui + 1, nxt);
;         const char* nA = has_next ? (const char*)g.A + (size_t)nxt.pm * tstep : cA; const char* nB = has_next ? (const char*)g.Bt + (size_t)nxt.pn * tstep : cB;
;         for (int t = 0; t < nt; t += 2) {
;             if constexpr (Epi::HAS_MID) { if (t == nt / 2) E.mid(acc, cur, wr, wc, fr, fq); }
;             const bool last = (t == nt - 2);
;             const char* a1 = cA + (size_t)(t + 1) * kstep;
;             const char* a2 = last ? nA : cA + (size_t)(t + 2) * kstep; const char* b2 = last ? nB : cB + (size_t)(t + 2) * kstep;
;     __device__ __forceinline__ void mid(f32x4 (&acc)[2][2][4][2], const pg8::Unit& u, int wr, int wc, int fr, int fq) const {
;     ...
;             for (int m = 0; m < 4; ++m) { const int row = u.pm * 256 + ai * 128 + wr * 64 + m * 16 + fr;
; #pragma unroll
;                 for (int bj = 0; bj < 2; ++bj) { const int col = u.pn * 256 + bj * 128 + wc * 32 + 8 * fq; const bf16_t* gp = G + (size_t)row * 2048 + col;
;                     f32x4 l0, l1, a0, a1; unpack_bf16x8(*(const u32x4*)gp, l0, l1); unpack_bf16x8(*(const u32x4*)(gp + 1024), a0, a1);
; #pragma unroll
;                     for (int i = 0; i < 4; ++i) { acc[ai][bj][m][0][i] *= l0[i] * __builtin_amdgcn_rcpf(fmaxf(a0[i], 1e-30f)); acc[ai][bj][m][1][i] *= l1[i] * __builtin_amdgcn_rcpf(fmaxf(a1[i], 1e-30f)); } } }
;     }
;     __device__ __forceinline__ void operator()(const f32x4 (&acc)[2][2][4][2], const pg8::Unit& u, int wr, int wc, int fr, int fq) const {
;         EPI_LOOP({ const int col = u.pn * 256 + tc; f32x4 a0, a1; unpack_bf16x8(*(const u32x4*)(G + (size_t)row * 2048 + 1024 + col), a0, a1);
.LBB0_665:
	s_ashr_i32 s15, s14, 31
	s_lshl_b64 s[16:17], s[14:15], 20
	s_add_u32 s16, s28, s16
	s_addc_u32 s17, s29, s17
	s_and_b64 s[18:19], s[2:3], exec
	s_cselect_b32 s15, s17, s21
	s_cselect_b32 s47, s16, s20
	s_ashr_i32 s13, s12, 31
	s_lshl_b64 s[18:19], s[12:13], 20
	s_add_u32 s18, s30, s18
	s_addc_u32 s19, s31, s19
	s_and_b64 s[26:27], s[2:3], exec
	s_cselect_b32 s13, s19, s23
	s_cselect_b32 s48, s18, s22
	s_lshl_b32 s24, s24, 4
	v_add_u32_e32 v154, s24, v133
	v_ashrrev_i32_e32 v155, 31, v154
	v_lshl_or_b32 v2, s25, 8, v182
	v_lshlrev_b64 v[0:1], 12, v[154:155]
	v_ashrrev_i32_e32 v3, 31, v2
	v_lshl_add_u64 v[0:1], s[4:5], 0, v[0:1]
	v_lshlrev_b64 v[152:153], 1, v[2:3]
	v_lshl_add_u64 v[156:157], v[0:1], 0, v[152:153]
	v_or_b32_e32 v0, 16, v133
	v_add_u32_e32 v0, s24, v0
	v_ashrrev_i32_e32 v1, 31, v0
	v_lshlrev_b64 v[0:1], 12, v[0:1]
	v_lshl_add_u64 v[0:1], s[4:5], 0, v[0:1]
	v_lshl_add_u64 v[158:159], v[0:1], 0, v[152:153]
	v_add_u32_e32 v0, s24, v176
	v_ashrrev_i32_e32 v1, 31, v0
	v_lshlrev_b64 v[0:1], 12, v[0:1]
	v_lshl_add_u64 v[0:1], s[4:5], 0, v[0:1]
	v_lshl_add_u64 v[160:161], v[0:1], 0, v[152:153]
	v_add_u32_e32 v0, s24, v177
	v_ashrrev_i32_e32 v1, 31, v0
	v_lshlrev_b64 v[0:1], 12, v[0:1]
	v_lshl_add_u64 v[0:1], s[4:5], 0, v[0:1]
	v_lshl_add_u64 v[162:163], v[0:1], 0, v[152:153]
	v_add_u32_e32 v0, s24, v178
	v_ashrrev_i32_e32 v1, 31, v0
	v_lshlrev_b64 v[0:1], 12, v[0:1]
	v_lshl_add_u64 v[0:1], s[4:5], 0, v[0:1]
	v_lshl_add_u64 v[164:165], v[0:1], 0, v[152:153]
	v_add_u32_e32 v0, s24, v179
	v_ashrrev_i32_e32 v1, 31, v0
	v_lshlrev_b64 v[0:1], 12, v[0:1]
	v_lshl_add_u64 v[0:1], s[4:5], 0, v[0:1]
	v_lshl_add_u64 v[166:167], v[0:1], 0, v[152:153]
	v_add_u32_e32 v0, s24, v180
	v_ashrrev_i32_e32 v1, 31, v0
	v_lshlrev_b64 v[0:1], 12, v[0:1]
	v_lshl_add_u64 v[0:1], s[4:5], 0, v[0:1]
	v_lshl_add_u64 v[168:169], v[0:1], 0, v[152:153]
	v_add_u32_e32 v0, s24, v181
	v_ashrrev_i32_e32 v1, 31, v0
	v_lshlrev_b64 v[0:1], 12, v[0:1]
	v_lshl_add_u64 v[0:1], s[4:5], 0, v[0:1]
	v_lshl_add_u64 v[170:171], v[0:1], 0, v[152:153]
	s_add_u32 s49, s22, 0x100
	v_mov_b32_e32 v0, 0
	v_lshl_add_u64 v[172:173], s[20:21], 0, v[144:145]
	v_lshl_add_u64 v[174:175], s[20:21], 0, v[146:147]
	s_addc_u32 s50, s23, 0
	s_mov_b32 s51, -2
	s_mov_b64 s[22:23], 0
	v_mov_b32_e32 v1, v0
	v_mov_b32_e32 v2, v0
	v_mov_b32_e32 v3, v0
	v_mov_b32_e32 v4, v0
	v_mov_b32_e32 v5, v0
	v_mov_b32_e32 v6, v0
	v_mov_b32_e32 v7, v0
	v_mov_b32_e32 v16, v0
	v_mov_b32_e32 v17, v0
	v_mov_b32_e32 v18, v0
	v_mov_b32_e32 v19, v0
	v_mov_b32_e32 v20, v0
	v_mov_b32_e32 v21, v0
	v_mov_b32_e32 v22, v0
	v_mov_b32_e32 v23, v0
	v_mov_b32_e32 v32, v0
	v_mov_b32_e32 v33, v0
	v_mov_b32_e32 v34, v0
	v_mov_b32_e32 v35, v0
	v_mov_b32_e32 v36, v0
	v_mov_b32_e32 v37, v0
	v_mov_b32_e32 v38, v0
	v_mov_b32_e32 v39, v0
	v_mov_b32_e32 v48, v0
	v_mov_b32_e32 v49, v0
	v_mov_b32_e32 v50, v0
	v_mov_b32_e32 v51, v0
	v_mov_b32_e32 v52, v0
	v_mov_b32_e32 v53, v0
	v_mov_b32_e32 v54, v0
	v_mov_b32_e32 v55, v0
	v_mov_b32_e32 v8, v0
	v_mov_b32_e32 v9, v0
	v_mov_b32_e32 v10, v0
	v_mov_b32_e32 v11, v0
	v_mov_b32_e32 v12, v0
	v_mov_b32_e32 v13, v0
	v_mov_b32_e32 v14, v0
	v_mov_b32_e32 v15, v0
	v_mov_b32_e32 v24, v0
	v_mov_b32_e32 v25, v0
	v_mov_b32_e32 v26, v0
	v_mov_b32_e32 v27, v0
	v_mov_b32_e32 v28, v0
	v_mov_b32_e32 v29, v0
	v_mov_b32_e32 v30, v0
	v_mov_b32_e32 v31, v0
	v_mov_b32_e32 v40, v0
	v_mov_b32_e32 v41, v0
	v_mov_b32_e32 v42, v0
	v_mov_b32_e32 v43, v0
	v_mov_b32_e32 v44, v0
	v_mov_b32_e32 v45, v0
	v_mov_b32_e32 v46, v0
	v_mov_b32_e32 v47, v0
	v_mov_b32_e32 v56, v0
	v_mov_b32_e32 v57, v0
	v_mov_b32_e32 v58, v0
	v_mov_b32_e32 v59, v0
	s_waitcnt vmcnt(0)
	v_mov_b32_e32 v60, v0
	v_mov_b32_e32 v61, v0
	v_mov_b32_e32 v62, v0
	v_mov_b32_e32 v63, v0
	v_mov_b32_e32 v64, v0
	v_mov_b32_e32 v65, v0
	v_mov_b32_e32 v66, v0
	v_mov_b32_e32 v67, v0
	v_mov_b32_e32 v68, v0
	v_mov_b32_e32 v69, v0
	v_mov_b32_e32 v70, v0
	v_mov_b32_e32 v71, v0
	v_mov_b32_e32 v80, v0
	v_mov_b32_e32 v81, v0
	v_mov_b32_e32 v82, v0
	v_mov_b32_e32 v83, v0
	v_mov_b32_e32 v84, v0
	v_mov_b32_e32 v85, v0
	v_mov_b32_e32 v86, v0
	v_mov_b32_e32 v87, v0
	v_mov_b32_e32 v96, v0
	v_mov_b32_e32 v97, v0
	v_mov_b32_e32 v98, v0
	v_mov_b32_e32 v99, v0
	v_mov_b32_e32 v100, v0
	v_mov_b32_e32 v101, v0
	v_mov_b32_e32 v102, v0
	v_mov_b32_e32 v103, v0
	v_mov_b32_e32 v112, v0
	v_mov_b32_e32 v113, v0
	v_mov_b32_e32 v114, v0
	v_mov_b32_e32 v115, v0
	v_mov_b32_e32 v116, v0
	v_mov_b32_e32 v117, v0
	v_mov_b32_e32 v118, v0
	v_mov_b32_e32 v119, v0
	v_mov_b32_e32 v72, v0
	v_mov_b32_e32 v73, v0
	v_mov_b32_e32 v74, v0
	v_mov_b32_e32 v75, v0
	v_mov_b32_e32 v76, v0
	v_mov_b32_e32 v77, v0
	v_mov_b32_e32 v78, v0
	v_mov_b32_e32 v79, v0
	v_mov_b32_e32 v88, v0
	v_mov_b32_e32 v89, v0
	v_mov_b32_e32 v90, v0
	v_mov_b32_e32 v91, v0
	v_mov_b32_e32 v92, v0
	v_mov_b32_e32 v93, v0
	v_mov_b32_e32 v94, v0
	v_mov_b32_e32 v95, v0
	v_mov_b32_e32 v104, v0
	v_mov_b32_e32 v105, v0
	v_mov_b32_e32 v106, v0
	v_mov_b32_e32 v107, v0
	v_mov_b32_e32 v108, v0
	v_mov_b32_e32 v109, v0
	v_mov_b32_e32 v110, v0
	v_mov_b32_e32 v111, v0
	v_mov_b32_e32 v120, v0
	v_mov_b32_e32 v121, v0
	v_mov_b32_e32 v122, v0
	v_mov_b32_e32 v123, v0
	v_mov_b32_e32 v124, v0
	v_mov_b32_e32 v125, v0
	v_mov_b32_e32 v126, v0
	v_mov_b32_e32 v127, v0
	s_branch .LBB0_667

; __device__ __forceinline__ u32x4 pack8(f32x4 a, f32x4 b) { u32x4 w; w.x = cvt_pk_bf16(a[0], a[1]); w.y = cvt_pk_bf16(a[2], a[3]); w.z = cvt_pk_bf16(b[0], b[1]); w.w = cvt_pk_bf16(b[2], b[3]); return w; }
; #define EPI_LOOP(...) _Pragma("unroll") for (int ai = 0; ai < 2; ++ai) _Pragma("unroll") for (int m = 0; m < 4; ++m) { const int row = u.pm * 256 + ai * 128 + wr * 64 + m * 16 + fr; \
;     _Pragma("unroll") for (int bj = 0; bj < 2; ++bj) { const int tc = bj * 128 + wc * 32 + 8 * fq; f32x4 v0 = acc[ai][bj][m][0], v1 = acc[ai][bj][m][1]; __VA_ARGS__ } }
;     __device__ __forceinline__ void operator()(const f32x4 (&acc)[2][2][4][2], const pg8::Unit& u, int wr, int wc, int fr, int fq) const {
;         EPI_LOOP({ const int col = u.pn * 256 + tc; f32x4 a0, a1; unpack_bf16x8(*(const u32x4*)(G + (size_t)row * 2048 + 1024 + col), a0, a1);
;                    _Pragma("unroll") for (int i = 0; i < 4; ++i) { a0[i] = fmaxf(a0[i], 1e-30f); a1[i] = fmaxf(a1[i], 1e-30f); }
;                    *(u32x4*)(MIXED + (size_t)row * D + col) = pack8(v0 * a0, v1 * a1); })
;     }
.LBB0_671:
	global_load_dwordx4 v[128:131], v[156:157], off offset:2048
	s_andn2_b64 vcc, exec, s[2:3]
	s_mov_b64 s[2:3], -1
	s_waitcnt vmcnt(0)
	v_lshlrev_b32_e32 v158, 16, v128
	v_and_b32_e32 v128, 0xffff0000, v128
	v_lshlrev_b32_e32 v159, 16, v129
	v_and_b32_e32 v129, 0xffff0000, v129
	v_lshlrev_b32_e32 v160, 16, v130
	v_and_b32_e32 v130, 0xffff0000, v130
	v_lshlrev_b32_e32 v161, 16, v131
	v_and_b32_e32 v131, 0xffff0000, v131
	v_max_f32_e32 v158, v158, v158
	v_max_f32_e32 v160, v160, v160
	v_max_f32_e32 v162, v128, v128
	v_max_f32_e32 v163, v130, v130
	v_max_f32_e32 v159, v159, v159
	v_max_f32_e32 v161, v161, v161
	v_max_f32_e32 v164, v129, v129
	v_max_f32_e32 v165, v131, v131
	v_max_f32_e32 v128, 0xda24260, v158
	v_max_f32_e32 v130, 0xda24260, v160
	v_max_f32_e32 v129, 0xda24260, v162
	v_max_f32_e32 v131, 0xda24260, v163
	v_max_f32_e32 v158, 0xda24260, v159
	v_max_f32_e32 v160, 0xda24260, v161
	v_max_f32_e32 v159, 0xda24260, v164
	v_max_f32_e32 v161, 0xda24260, v165
	v_pk_mul_f32 v[126:127], v[126:127], v[158:159]
	v_pk_mul_f32 v[124:125], v[124:125], v[128:129]
	v_pk_mul_f32 v[128:129], v[122:123], v[160:161]
	v_pk_mul_f32 v[122:123], v[120:121], v[130:131]
	v_cvt_pk_bf16_f32 v120, v124, v125
	v_cvt_pk_bf16_f32 v121, v126, v127
	v_add_u32_e32 v130, 16, v154
	v_cvt_pk_bf16_f32 v122, v122, v123
	v_cvt_pk_bf16_f32 v123, v128, v129
	global_load_dwordx4 v[124:127], v[156:157], off offset:2304
	v_lshlrev_b64 v[128:129], 11, v[154:155]
	v_lshl_add_u64 v[128:129], s[6:7], 0, v[128:129]
	v_lshl_add_u64 v[128:129], v[128:129], 0, v[152:153]
	v_ashrrev_i32_e32 v131, 31, v130
	global_store_dwordx4 v[128:129], v[120:123], off
	v_lshlrev_b64 v[156:157], 12, v[130:131]
	v_lshl_add_u64 v[156:157], s[4:5], 0, v[156:157]
	v_lshl_add_u64 v[156:157], v[156:157], 0, v[152:153]
	s_waitcnt vmcnt(1)
	v_lshlrev_b32_e32 v120, 16, v124
	v_and_b32_e32 v121, 0xffff0000, v124
	v_lshlrev_b32_e32 v122, 16, v125
	v_and_b32_e32 v123, 0xffff0000, v125
	v_lshlrev_b32_e32 v124, 16, v126
	v_and_b32_e32 v125, 0xffff0000, v126
	v_lshlrev_b32_e32 v126, 16, v127
	v_and_b32_e32 v127, 0xffff0000, v127
	v_max_f32_e32 v120, v120, v120
	v_max_f32_e32 v124, v124, v124
	v_max_f32_e32 v121, v121, v121
	v_max_f32_e32 v125, v125, v125
	v_max_f32_e32 v155, v122, v122
	v_max_f32_e32 v126, v126, v126
	v_max_f32_e32 v158, v123, v123
	v_max_f32_e32 v127, v127, v127
	v_max_f32_e32 v120, 0xda24260, v120
	v_max_f32_e32 v122, 0xda24260, v124
	v_max_f32_e32 v121, 0xda24260, v121
	v_max_f32_e32 v123, 0xda24260, v125
	v_max_f32_e32 v124, 0xda24260, v155
	v_max_f32_e32 v126, 0xda24260, v126
	v_max_f32_e32 v125, 0xda24260, v158
	v_max_f32_e32 v127, 0xda24260, v127
	v_pk_mul_f32 v[118:119], v[118:119], v[124:125]
	v_pk_mul_f32 v[116:117], v[116:117], v[120:121]
	v_pk_mul_f32 v[120:121], v[114:115], v[126:127]
	v_pk_mul_f32 v[114:115], v[112:113], v[122:123]
	v_cvt_pk_bf16_f32 v112, v116, v117
	v_cvt_pk_bf16_f32 v113, v118, v119
	s_nop 0
	v_cvt_pk_bf16_f32 v114, v114, v115
	v_cvt_pk_bf16_f32 v115, v120, v121
	global_load_dwordx4 v[116:119], v[156:157], off offset:2048
	s_nop 0
	global_store_dwordx4 v[128:129], v[112:115], off offset:256
	s_waitcnt vmcnt(1)
	s_nop 0
	v_lshlrev_b32_e32 v112, 16, v116
	v_and_b32_e32 v113, 0xffff0000, v116
	v_lshlrev_b32_e32 v114, 16, v117
	v_and_b32_e32 v115, 0xffff0000, v117
	v_lshlrev_b32_e32 v116, 16, v118
	v_and_b32_e32 v117, 0xffff0000, v118
	v_lshlrev_b32_e32 v118, 16, v119
	v_and_b32_e32 v119, 0xffff0000, v119
	v_max_f32_e32 v112, v112, v112
	v_max_f32_e32 v116, v116, v116
	v_max_f32_e32 v113, v113, v113
	v_max_f32_e32 v117, v117, v117
	v_max_f32_e32 v120, v114, v114
	v_max_f32_e32 v118, v118, v118
	v_max_f32_e32 v121, v115, v115
	v_max_f32_e32 v119, v119, v119
	v_max_f32_e32 v112, 0xda24260, v112
	v_max_f32_e32 v114, 0xda24260, v116
	v_max_f32_e32 v113, 0xda24260, v113
	v_max_f32_e32 v115, 0xda24260, v117
	v_max_f32_e32 v116, 0xda24260, v120
	v_max_f32_e32 v118, 0xda24260, v118
	v_max_f32_e32 v117, 0xda24260, v121
	v_max_f32_e32 v119, 0xda24260, v119
	v_pk_mul_f32 v[110:111], v[110:111], v[116:117]
	v_pk_mul_f32 v[108:109], v[108:109], v[112:113]
	v_pk_mul_f32 v[112:113], v[106:107], v[118:119]
	v_pk_mul_f32 v[106:107], v[104:105], v[114:115]
	v_cvt_pk_bf16_f32 v104, v108, v109
	v_cvt_pk_bf16_f32 v105, v110, v111
	v_lshlrev_b64 v[114:115], 11, v[130:131]
	v_cvt_pk_bf16_f32 v106, v106, v107
	v_cvt_pk_bf16_f32 v107, v112, v113
	global_load_dwordx4 v[108:111], v[156:157], off offset:2304
	v_lshl_add_u64 v[114:115], s[6:7], 0, v[114:115]
	v_add_u32_e32 v112, 32, v154
	v_lshl_add_u64 v[114:115], v[114:115], 0, v[152:153]
	v_ashrrev_i32_e32 v113, 31, v112
	global_store_dwordx4 v[114:115], v[104:107], off
	v_lshlrev_b64 v[116:117], 12, v[112:113]
	v_lshl_add_u64 v[116:117], s[4:5], 0, v[116:117]
	v_lshl_add_u64 v[116:117], v[116:117], 0, v[152:153]
	s_waitcnt vmcnt(1)
	v_lshlrev_b32_e32 v104, 16, v108
	v_and_b32_e32 v105, 0xffff0000, v108
	v_lshlrev_b32_e32 v106, 16, v109
	v_and_b32_e32 v107, 0xffff0000, v109
	v_lshlrev_b32_e32 v108, 16, v110
	v_and_b32_e32 v109, 0xffff0000, v110
	v_lshlrev_b32_e32 v110, 16, v111
	v_and_b32_e32 v111, 0xffff0000, v111
	v_max_f32_e32 v104, v104, v104
	v_max_f32_e32 v108, v108, v108
	v_max_f32_e32 v105, v105, v105
	v_max_f32_e32 v109, v109, v109
	v_max_f32_e32 v118, v106, v106
	v_max_f32_e32 v110, v110, v110
	v_max_f32_e32 v119, v107, v107
	v_max_f32_e32 v111, v111, v111
	v_max_f32_e32 v104, 0xda24260, v104
	v_max_f32_e32 v106, 0xda24260, v108
	v_max_f32_e32 v105, 0xda24260, v105
	v_max_f32_e32 v107, 0xda24260, v109
	v_max_f32_e32 v108, 0xda24260, v118
	v_max_f32_e32 v110, 0xda24260, v110
	v_max_f32_e32 v109, 0xda24260, v119
	v_max_f32_e32 v111, 0xda24260, v111
	v_pk_mul_f32 v[102:103], v[102:103], v[108:109]
	v_pk_mul_f32 v[100:101], v[100:101], v[104:105]
	v_pk_mul_f32 v[104:105], v[98:99], v[110:111]
	v_pk_mul_f32 v[98:99], v[96:97], v[106:107]
	v_cvt_pk_bf16_f32 v96, v100, v101
	v_cvt_pk_bf16_f32 v97, v102, v103
	s_nop 0
	v_cvt_pk_bf16_f32 v98, v98, v99
	v_cvt_pk_bf16_f32 v99, v104, v105
	global_load_dwordx4 v[100:103], v[116:117], off offset:2048
	s_nop 0
	global_store_dwordx4 v[114:115], v[96:99], off offset:256
	s_waitcnt vmcnt(1)
; __device__ __forceinline__ u32x4 pack8(f32x4 a, f32x4 b) { u32x4 w; w.x = cvt_pk_bf16(a[0], a[1]); w.y = cvt_pk_bf16(a[2], a[3]); w.z = cvt_pk_bf16(b[0], b[1]); w.w = cvt_pk_bf16(b[2], b[3]); return w; }
; #define EPI_LOOP(...) _Pragma("unroll") for (int ai = 0; ai < 2; ++ai) _Pragma("unroll") for (int m = 0; m < 4; ++m) { const int row = u.pm * 256 + ai * 128 + wr * 64 + m * 16 + fr; \
;     _Pragma("unroll") for (int bj = 0; bj < 2; ++bj) { const int tc = bj * 128 + wc * 32 + 8 * fq; f32x4 v0 = acc[ai][bj][m][0], v1 = acc[ai][bj][m][1]; __VA_ARGS__ } }
;     __device__ __forceinline__ void operator()(const f32x4 (&acc)[2][2][4][2], const pg8::Unit& u, int wr, int wc, int fr, int fq) const {
;         EPI_LOOP({ const int col = u.pn * 256 + tc; f32x4 a0, a1; unpack_bf16x8(*(const u32x4*)(G + (size_t)row * 2048 + 1024 + col), a0, a1);
;                    _Pragma("unroll") for (int i = 0; i < 4; ++i) { a0[i] = fmaxf(a0[i], 1e-30f); a1[i] = fmaxf(a1[i], 1e-30f); }
;                    *(u32x4*)(MIXED + (size_t)row * D + col) = pack8(v0 * a0, v1 * a1); })
;     }
	s_nop 0
	v_lshlrev_b32_e32 v96, 16, v100
	v_and_b32_e32 v97, 0xffff0000, v100
	v_lshlrev_b32_e32 v98, 16, v101
	v_and_b32_e32 v99, 0xffff0000, v101
	v_lshlrev_b32_e32 v100, 16, v102
	v_and_b32_e32 v101, 0xffff0000, v102
	v_lshlrev_b32_e32 v102, 16, v103
	v_and_b32_e32 v103, 0xffff0000, v103
	v_max_f32_e32 v96, v96, v96
	v_max_f32_e32 v100, v100, v100
	v_max_f32_e32 v97, v97, v97
	v_max_f32_e32 v101, v101, v101
	v_max_f32_e32 v104, v98, v98
	v_max_f32_e32 v102, v102, v102
	v_max_f32_e32 v105, v99, v99
	v_max_f32_e32 v103, v103, v103
	v_max_f32_e32 v96, 0xda24260, v96
	v_max_f32_e32 v98, 0xda24260, v100
	v_max_f32_e32 v97, 0xda24260, v97
	v_max_f32_e32 v99, 0xda24260, v101
	v_max_f32_e32 v100, 0xda24260, v104
	v_max_f32_e32 v102, 0xda24260, v102
	v_max_f32_e32 v101, 0xda24260, v105
	v_max_f32_e32 v103, 0xda24260, v103
	v_pk_mul_f32 v[94:95], v[94:95], v[100:101]
	v_pk_mul_f32 v[92:93], v[92:93], v[96:97]
	v_pk_mul_f32 v[96:97], v[90:91], v[102:103]
	v_pk_mul_f32 v[90:91], v[88:89], v[98:99]
	v_cvt_pk_bf16_f32 v88, v92, v93
	v_cvt_pk_bf16_f32 v89, v94, v95
	v_lshlrev_b64 v[98:99], 11, v[112:113]
	v_cvt_pk_bf16_f32 v90, v90, v91
	v_cvt_pk_bf16_f32 v91, v96, v97
	global_load_dwordx4 v[92:95], v[116:117], off offset:2304
	v_lshl_add_u64 v[98:99], s[6:7], 0, v[98:99]
	v_add_u32_e32 v96, 48, v154
	v_lshl_add_u64 v[98:99], v[98:99], 0, v[152:153]
	v_ashrrev_i32_e32 v97, 31, v96
	global_store_dwordx4 v[98:99], v[88:91], off
	v_lshlrev_b64 v[100:101], 12, v[96:97]
	v_lshl_add_u64 v[100:101], s[4:5], 0, v[100:101]
	v_lshl_add_u64 v[100:101], v[100:101], 0, v[152:153]
	s_waitcnt vmcnt(1)
	v_lshlrev_b32_e32 v88, 16, v92
	v_and_b32_e32 v89, 0xffff0000, v92
	v_lshlrev_b32_e32 v90, 16, v93
	v_and_b32_e32 v91, 0xffff0000, v93
	v_lshlrev_b32_e32 v92, 16, v94
	v_and_b32_e32 v93, 0xffff0000, v94
	v_lshlrev_b32_e32 v94, 16, v95
	v_and_b32_e32 v95, 0xffff0000, v95
	v_max_f32_e32 v88, v88, v88
	v_max_f32_e32 v92, v92, v92
	v_max_f32_e32 v89, v89, v89
	v_max_f32_e32 v93, v93, v93
	v_max_f32_e32 v102, v90, v90
	v_max_f32_e32 v94, v94, v94
	v_max_f32_e32 v103, v91, v91
	v_max_f32_e32 v95, v95, v95
	v_max_f32_e32 v88, 0xda24260, v88
	v_max_f32_e32 v90, 0xda24260, v92
	v_max_f32_e32 v89, 0xda24260, v89
	v_max_f32_e32 v91, 0xda24260, v93
	v_max_f32_e32 v92, 0xda24260, v102
	v_max_f32_e32 v94, 0xda24260, v94
	v_max_f32_e32 v93, 0xda24260, v103
	v_max_f32_e32 v95, 0xda24260, v95
	v_pk_mul_f32 v[86:87], v[86:87], v[92:93]
	v_pk_mul_f32 v[84:85], v[84:85], v[88:89]
	v_pk_mul_f32 v[88:89], v[82:83], v[94:95]
	v_pk_mul_f32 v[82:83], v[80:81], v[90:91]
	v_cvt_pk_bf16_f32 v80, v84, v85
	v_cvt_pk_bf16_f32 v81, v86, v87
	s_nop 0
	v_cvt_pk_bf16_f32 v82, v82, v83
	v_cvt_pk_bf16_f32 v83, v88, v89
	global_load_dwordx4 v[84:87], v[100:101], off offset:2048
	s_nop 0
	global_store_dwordx4 v[98:99], v[80:83], off offset:256
	s_waitcnt vmcnt(1)
	s_nop 0
	v_lshlrev_b32_e32 v80, 16, v84
	v_and_b32_e32 v81, 0xffff0000, v84
	v_lshlrev_b32_e32 v82, 16, v85
	v_and_b32_e32 v83, 0xffff0000, v85
	v_lshlrev_b32_e32 v84, 16, v86
	v_and_b32_e32 v85, 0xffff0000, v86
	v_lshlrev_b32_e32 v86, 16, v87
	v_and_b32_e32 v87, 0xffff0000, v87
	v_max_f32_e32 v80, v80, v80
	v_max_f32_e32 v84, v84, v84
	v_max_f32_e32 v81, v81, v81
	v_max_f32_e32 v85, v85, v85
	v_max_f32_e32 v88, v82, v82
	v_max_f32_e32 v86, v86, v86
	v_max_f32_e32 v89, v83, v83
	v_max_f32_e32 v87, v87, v87
	v_max_f32_e32 v80, 0xda24260, v80
	v_max_f32_e32 v82, 0xda24260, v84
	v_max_f32_e32 v81, 0xda24260, v81
	v_max_f32_e32 v83, 0xda24260, v85
	v_max_f32_e32 v84, 0xda24260, v88
	v_max_f32_e32 v86, 0xda24260, v86
	v_max_f32_e32 v85, 0xda24260, v89
	v_max_f32_e32 v87, 0xda24260, v87
	v_pk_mul_f32 v[78:79], v[78:79], v[84:85]
	v_pk_mul_f32 v[76:77], v[76:77], v[80:81]
	v_pk_mul_f32 v[80:81], v[74:75], v[86:87]
	v_pk_mul_f32 v[74:75], v[72:73], v[82:83]
	v_cvt_pk_bf16_f32 v72, v76, v77
	v_cvt_pk_bf16_f32 v73, v78, v79
	v_lshlrev_b64 v[82:83], 11, v[96:97]
	v_cvt_pk_bf16_f32 v74, v74, v75
	v_cvt_pk_bf16_f32 v75, v80, v81
	global_load_dwordx4 v[76:79], v[100:101], off offset:2304
	v_lshl_add_u64 v[82:83], s[6:7], 0, v[82:83]
	v_add_u32_e32 v80, 0x80, v154
	v_lshl_add_u64 v[82:83], v[82:83], 0, v[152:153]
	v_ashrrev_i32_e32 v81, 31, v80
	global_store_dwordx4 v[82:83], v[72:75], off
	v_lshlrev_b64 v[84:85], 12, v[80:81]
	v_lshl_add_u64 v[84:85], s[4:5], 0, v[84:85]
	v_lshl_add_u64 v[84:85], v[84:85], 0, v[152:153]
	s_waitcnt vmcnt(1)
	v_lshlrev_b32_e32 v72, 16, v76
	v_and_b32_e32 v73, 0xffff0000, v76
	v_lshlrev_b32_e32 v74, 16, v77
	v_and_b32_e32 v75, 0xffff0000, v77
	v_lshlrev_b32_e32 v76, 16, v78
	v_and_b32_e32 v77, 0xffff0000, v78
	v_lshlrev_b32_e32 v78, 16, v79
	v_and_b32_e32 v79, 0xffff0000, v79
	v_max_f32_e32 v72, v72, v72
	v_max_f32_e32 v76, v76, v76
	v_max_f32_e32 v73, v73, v73
	v_max_f32_e32 v77, v77, v77
	v_max_f32_e32 v86, v74, v74
	v_max_f32_e32 v78, v78, v78
	v_max_f32_e32 v87, v75, v75
	v_max_f32_e32 v79, v79, v79
	v_max_f32_e32 v72, 0xda24260, v72
	v_max_f32_e32 v74, 0xda24260, v76
	v_max_f32_e32 v73, 0xda24260, v73
	v_max_f32_e32 v75, 0xda24260, v77
	v_max_f32_e32 v76, 0xda24260, v86
	v_max_f32_e32 v78, 0xda24260, v78
	v_max_f32_e32 v77, 0xda24260, v87
	v_max_f32_e32 v79, 0xda24260, v79
	v_pk_mul_f32 v[70:71], v[70:71], v[76:77]
	v_pk_mul_f32 v[68:69], v[68:69], v[72:73]
	v_pk_mul_f32 v[72:73], v[66:67], v[78:79]
	v_pk_mul_f32 v[66:67], v[64:65], v[74:75]
	v_cvt_pk_bf16_f32 v64, v68, v69
	v_cvt_pk_bf16_f32 v65, v70, v71
	s_nop 0
	v_cvt_pk_bf16_f32 v66, v66, v67
	v_cvt_pk_bf16_f32 v67, v72, v73
	global_load_dwordx4 v[68:71], v[84:85], off offset:2048
	s_nop 0
	global_store_dwordx4 v[82:83], v[64:67], off offset:256
	s_waitcnt vmcnt(1)
; __device__ __forceinline__ u32x4 pack8(f32x4 a, f32x4 b) { u32x4 w; w.x = cvt_pk_bf16(a[0], a[1]); w.y = cvt_pk_bf16(a[2], a[3]); w.z = cvt_pk_bf16(b[0], b[1]); w.w = cvt_pk_bf16(b[2], b[3]); return w; }
; #define EPI_LOOP(...) _Pragma("unroll") for (int ai = 0; ai < 2; ++ai) _Pragma("unroll") for (int m = 0; m < 4; ++m) { const int row = u.pm * 256 + ai * 128 + wr * 64 + m * 16 + fr; \
;     _Pragma("unroll") for (int bj = 0; bj < 2; ++bj) { const int tc = bj * 128 + wc * 32 + 8 * fq; f32x4 v0 = acc[ai][bj][m][0], v1 = acc[ai][bj][m][1]; __VA_ARGS__ } }
;     __device__ __forceinline__ void operator()(const f32x4 (&acc)[2][2][4][2], const pg8::Unit& u, int wr, int wc, int fr, int fq) const {
;         EPI_LOOP({ const int col = u.pn * 256 + tc; f32x4 a0, a1; unpack_bf16x8(*(const u32x4*)(G + (size_t)row * 2048 + 1024 + col), a0, a1);
;                    _Pragma("unroll") for (int i = 0; i < 4; ++i) { a0[i] = fmaxf(a0[i], 1e-30f); a1[i] = fmaxf(a1[i], 1e-30f); }
;                    *(u32x4*)(MIXED + (size_t)row * D + col) = pack8(v0 * a0, v1 * a1); })
;     }
	s_nop 0
	v_lshlrev_b32_e32 v64, 16, v68
	v_and_b32_e32 v65, 0xffff0000, v68
	v_lshlrev_b32_e32 v66, 16, v69
	v_and_b32_e32 v67, 0xffff0000, v69
	v_lshlrev_b32_e32 v68, 16, v70
	v_and_b32_e32 v69, 0xffff0000, v70
	v_lshlrev_b32_e32 v70, 16, v71
	v_and_b32_e32 v71, 0xffff0000, v71
	v_max_f32_e32 v64, v64, v64
	v_max_f32_e32 v68, v68, v68
	v_max_f32_e32 v65, v65, v65
	v_max_f32_e32 v69, v69, v69
	v_max_f32_e32 v72, v66, v66
	v_max_f32_e32 v70, v70, v70
	v_max_f32_e32 v73, v67, v67
	v_max_f32_e32 v71, v71, v71
	v_max_f32_e32 v64, 0xda24260, v64
	v_max_f32_e32 v66, 0xda24260, v68
	v_max_f32_e32 v65, 0xda24260, v65
	v_max_f32_e32 v67, 0xda24260, v69
	v_max_f32_e32 v68, 0xda24260, v72
	v_max_f32_e32 v70, 0xda24260, v70
	v_max_f32_e32 v69, 0xda24260, v73
	v_max_f32_e32 v71, 0xda24260, v71
	v_pk_mul_f32 v[62:63], v[62:63], v[68:69]
	v_pk_mul_f32 v[60:61], v[60:61], v[64:65]
	v_pk_mul_f32 v[64:65], v[58:59], v[70:71]
	v_pk_mul_f32 v[58:59], v[56:57], v[66:67]
	v_cvt_pk_bf16_f32 v56, v60, v61
	v_cvt_pk_bf16_f32 v57, v62, v63
	v_lshlrev_b64 v[66:67], 11, v[80:81]
	v_cvt_pk_bf16_f32 v58, v58, v59
	v_cvt_pk_bf16_f32 v59, v64, v65
	global_load_dwordx4 v[60:63], v[84:85], off offset:2304
	v_lshl_add_u64 v[66:67], s[6:7], 0, v[66:67]
	v_add_u32_e32 v64, 0x90, v154
	v_lshl_add_u64 v[66:67], v[66:67], 0, v[152:153]
	v_ashrrev_i32_e32 v65, 31, v64
	global_store_dwordx4 v[66:67], v[56:59], off
	v_lshlrev_b64 v[68:69], 12, v[64:65]
	v_lshl_add_u64 v[68:69], s[4:5], 0, v[68:69]
	v_lshl_add_u64 v[68:69], v[68:69], 0, v[152:153]
	s_waitcnt vmcnt(1)
	v_lshlrev_b32_e32 v56, 16, v60
	v_and_b32_e32 v57, 0xffff0000, v60
	v_lshlrev_b32_e32 v58, 16, v61
	v_and_b32_e32 v59, 0xffff0000, v61
	v_lshlrev_b32_e32 v60, 16, v62
	v_and_b32_e32 v61, 0xffff0000, v62
	v_lshlrev_b32_e32 v62, 16, v63
	v_and_b32_e32 v63, 0xffff0000, v63
	v_max_f32_e32 v56, v56, v56
	v_max_f32_e32 v60, v60, v60
	v_max_f32_e32 v57, v57, v57
	v_max_f32_e32 v61, v61, v61
	v_max_f32_e32 v70, v58, v58
	v_max_f32_e32 v62, v62, v62
	v_max_f32_e32 v71, v59, v59
	v_max_f32_e32 v63, v63, v63
	v_max_f32_e32 v56, 0xda24260, v56
	v_max_f32_e32 v58, 0xda24260, v60
	v_max_f32_e32 v57, 0xda24260, v57
	v_max_f32_e32 v59, 0xda24260, v61
	v_max_f32_e32 v60, 0xda24260, v70
	v_max_f32_e32 v62, 0xda24260, v62
	v_max_f32_e32 v61, 0xda24260, v71
	v_max_f32_e32 v63, 0xda24260, v63
	v_pk_mul_f32 v[54:55], v[54:55], v[60:61]
	v_pk_mul_f32 v[52:53], v[52:53], v[56:57]
	v_pk_mul_f32 v[56:57], v[50:51], v[62:63]
	v_pk_mul_f32 v[50:51], v[48:49], v[58:59]
	v_cvt_pk_bf16_f32 v48, v52, v53
	v_cvt_pk_bf16_f32 v49, v54, v55
	s_nop 0
	v_cvt_pk_bf16_f32 v50, v50, v51
	v_cvt_pk_bf16_f32 v51, v56, v57
	global_load_dwordx4 v[52:55], v[68:69], off offset:2048
	s_nop 0
	global_store_dwordx4 v[66:67], v[48:51], off offset:256
	s_waitcnt vmcnt(1)
	s_nop 0
	v_lshlrev_b32_e32 v48, 16, v52
	v_and_b32_e32 v49, 0xffff0000, v52
	v_lshlrev_b32_e32 v50, 16, v53
	v_and_b32_e32 v51, 0xffff0000, v53
	v_lshlrev_b32_e32 v52, 16, v54
	v_and_b32_e32 v53, 0xffff0000, v54
	v_lshlrev_b32_e32 v54, 16, v55
	v_and_b32_e32 v55, 0xffff0000, v55
	v_max_f32_e32 v48, v48, v48
	v_max_f32_e32 v52, v52, v52
	v_max_f32_e32 v49, v49, v49
	v_max_f32_e32 v53, v53, v53
	v_max_f32_e32 v56, v50, v50
	v_max_f32_e32 v54, v54, v54
	v_max_f32_e32 v57, v51, v51
	v_max_f32_e32 v55, v55, v55
	v_max_f32_e32 v48, 0xda24260, v48
	v_max_f32_e32 v50, 0xda24260, v52
	v_max_f32_e32 v49, 0xda24260, v49
	v_max_f32_e32 v51, 0xda24260, v53
	v_max_f32_e32 v52, 0xda24260, v56
	v_max_f32_e32 v54, 0xda24260, v54
	v_max_f32_e32 v53, 0xda24260, v57
	v_max_f32_e32 v55, 0xda24260, v55
	v_pk_mul_f32 v[46:47], v[46:47], v[52:53]
	v_pk_mul_f32 v[44:45], v[44:45], v[48:49]
	v_pk_mul_f32 v[48:49], v[42:43], v[54:55]
	v_pk_mul_f32 v[42:43], v[40:41], v[50:51]
	v_cvt_pk_bf16_f32 v40, v44, v45
	v_cvt_pk_bf16_f32 v41, v46, v47
	v_lshlrev_b64 v[50:51], 11, v[64:65]
	v_cvt_pk_bf16_f32 v42, v42, v43
	v_cvt_pk_bf16_f32 v43, v48, v49
	global_load_dwordx4 v[44:47], v[68:69], off offset:2304
	v_lshl_add_u64 v[50:51], s[6:7], 0, v[50:51]
	v_add_u32_e32 v48, 0xa0, v154
	v_lshl_add_u64 v[50:51], v[50:51], 0, v[152:153]
	v_ashrrev_i32_e32 v49, 31, v48
	global_store_dwordx4 v[50:51], v[40:43], off
	v_lshlrev_b64 v[52:53], 12, v[48:49]
	v_lshl_add_u64 v[52:53], s[4:5], 0, v[52:53]
	v_lshl_add_u64 v[52:53], v[52:53], 0, v[152:153]
	s_waitcnt vmcnt(1)
	v_lshlrev_b32_e32 v40, 16, v44
	v_and_b32_e32 v41, 0xffff0000, v44
	v_lshlrev_b32_e32 v42, 16, v45
	v_and_b32_e32 v43, 0xffff0000, v45
	v_lshlrev_b32_e32 v44, 16, v46
	v_and_b32_e32 v45, 0xffff0000, v46
	v_lshlrev_b32_e32 v46, 16, v47
	v_and_b32_e32 v47, 0xffff0000, v47
	v_max_f32_e32 v40, v40, v40
	v_max_f32_e32 v44, v44, v44
	v_max_f32_e32 v41, v41, v41
	v_max_f32_e32 v45, v45, v45
	v_max_f32_e32 v54, v42, v42
	v_max_f32_e32 v46, v46, v46
	v_max_f32_e32 v55, v43, v43
	v_max_f32_e32 v47, v47, v47
	v_max_f32_e32 v40, 0xda24260, v40
	v_max_f32_e32 v42, 0xda24260, v44
	v_max_f32_e32 v41, 0xda24260, v41
	v_max_f32_e32 v43, 0xda24260, v45
	v_max_f32_e32 v44, 0xda24260, v54
	v_max_f32_e32 v46, 0xda24260, v46
	v_max_f32_e32 v45, 0xda24260, v55
	v_max_f32_e32 v47, 0xda24260, v47
	v_pk_mul_f32 v[38:39], v[38:39], v[44:45]
	v_pk_mul_f32 v[36:37], v[36:37], v[40:41]
	v_pk_mul_f32 v[40:41], v[34:35], v[46:47]
	v_pk_mul_f32 v[34:35], v[32:33], v[42:43]
	v_cvt_pk_bf16_f32 v32, v36, v37
	v_cvt_pk_bf16_f32 v33, v38, v39
	s_nop 0
	v_cvt_pk_bf16_f32 v34, v34, v35
	v_cvt_pk_bf16_f32 v35, v40, v41
	global_load_dwordx4 v[36:39], v[52:53], off offset:2048
	s_nop 0
	global_store_dwordx4 v[50:51], v[32:35], off offset:256
	s_waitcnt vmcnt(1)
; __device__ __forceinline__ u32x4 pack8(f32x4 a, f32x4 b) { u32x4 w; w.x = cvt_pk_bf16(a[0], a[1]); w.y = cvt_pk_bf16(a[2], a[3]); w.z = cvt_pk_bf16(b[0], b[1]); w.w = cvt_pk_bf16(b[2], b[3]); return w; }
; #define EPI_LOOP(...) _Pragma("unroll") for (int ai = 0; ai < 2; ++ai) _Pragma("unroll") for (int m = 0; m < 4; ++m) { const int row = u.pm * 256 + ai * 128 + wr * 64 + m * 16 + fr; \
;     _Pragma("unroll") for (int bj = 0; bj < 2; ++bj) { const int tc = bj * 128 + wc * 32 + 8 * fq; f32x4 v0 = acc[ai][bj][m][0], v1 = acc[ai][bj][m][1]; __VA_ARGS__ } }
;     __device__ __forceinline__ void operator()(const f32x4 (&acc)[2][2][4][2], const pg8::Unit& u, int wr, int wc, int fr, int fq) const {
;         EPI_LOOP({ const int col = u.pn * 256 + tc; f32x4 a0, a1; unpack_bf16x8(*(const u32x4*)(G + (size_t)row * 2048 + 1024 + col), a0, a1);
;                    _Pragma("unroll") for (int i = 0; i < 4; ++i) { a0[i] = fmaxf(a0[i], 1e-30f); a1[i] = fmaxf(a1[i], 1e-30f); }
;                    *(u32x4*)(MIXED + (size_t)row * D + col) = pack8(v0 * a0, v1 * a1); })
;     }
	s_nop 0
	v_lshlrev_b32_e32 v32, 16, v36
	v_and_b32_e32 v33, 0xffff0000, v36
	v_lshlrev_b32_e32 v34, 16, v37
	v_and_b32_e32 v35, 0xffff0000, v37
	v_lshlrev_b32_e32 v36, 16, v38
	v_and_b32_e32 v37, 0xffff0000, v38
	v_lshlrev_b32_e32 v38, 16, v39
	v_and_b32_e32 v39, 0xffff0000, v39
	v_max_f32_e32 v32, v32, v32
	v_max_f32_e32 v36, v36, v36
	v_max_f32_e32 v33, v33, v33
	v_max_f32_e32 v37, v37, v37
	v_max_f32_e32 v40, v34, v34
	v_max_f32_e32 v38, v38, v38
	v_max_f32_e32 v41, v35, v35
	v_max_f32_e32 v39, v39, v39
	v_max_f32_e32 v32, 0xda24260, v32
	v_max_f32_e32 v34, 0xda24260, v36
	v_max_f32_e32 v33, 0xda24260, v33
	v_max_f32_e32 v35, 0xda24260, v37
	v_max_f32_e32 v36, 0xda24260, v40
	v_max_f32_e32 v38, 0xda24260, v38
	v_max_f32_e32 v37, 0xda24260, v41
	v_max_f32_e32 v39, 0xda24260, v39
	v_pk_mul_f32 v[30:31], v[30:31], v[36:37]
	v_pk_mul_f32 v[28:29], v[28:29], v[32:33]
	v_pk_mul_f32 v[32:33], v[26:27], v[38:39]
	v_pk_mul_f32 v[26:27], v[24:25], v[34:35]
	v_cvt_pk_bf16_f32 v24, v28, v29
	v_cvt_pk_bf16_f32 v25, v30, v31
	v_lshlrev_b64 v[34:35], 11, v[48:49]
	v_cvt_pk_bf16_f32 v26, v26, v27
	v_cvt_pk_bf16_f32 v27, v32, v33
	global_load_dwordx4 v[28:31], v[52:53], off offset:2304
	v_lshl_add_u64 v[34:35], s[6:7], 0, v[34:35]
	v_add_u32_e32 v32, 0xb0, v154
	v_lshl_add_u64 v[34:35], v[34:35], 0, v[152:153]
	v_ashrrev_i32_e32 v33, 31, v32
	global_store_dwordx4 v[34:35], v[24:27], off
	v_lshlrev_b64 v[36:37], 12, v[32:33]
	v_lshl_add_u64 v[36:37], s[4:5], 0, v[36:37]
	v_lshl_add_u64 v[36:37], v[36:37], 0, v[152:153]
	s_waitcnt vmcnt(1)
	v_lshlrev_b32_e32 v24, 16, v28
	v_and_b32_e32 v25, 0xffff0000, v28
	v_lshlrev_b32_e32 v26, 16, v29
	v_and_b32_e32 v27, 0xffff0000, v29
	v_lshlrev_b32_e32 v28, 16, v30
	v_and_b32_e32 v29, 0xffff0000, v30
	v_lshlrev_b32_e32 v30, 16, v31
	v_and_b32_e32 v31, 0xffff0000, v31
	v_max_f32_e32 v24, v24, v24
	v_max_f32_e32 v28, v28, v28
	v_max_f32_e32 v25, v25, v25
	v_max_f32_e32 v29, v29, v29
	v_max_f32_e32 v38, v26, v26
	v_max_f32_e32 v30, v30, v30
	v_max_f32_e32 v39, v27, v27
	v_max_f32_e32 v31, v31, v31
	v_max_f32_e32 v24, 0xda24260, v24
	v_max_f32_e32 v26, 0xda24260, v28
	v_max_f32_e32 v25, 0xda24260, v25
	v_max_f32_e32 v27, 0xda24260, v29
	v_max_f32_e32 v28, 0xda24260, v38
	v_max_f32_e32 v30, 0xda24260, v30
	v_max_f32_e32 v29, 0xda24260, v39
	v_max_f32_e32 v31, 0xda24260, v31
	v_pk_mul_f32 v[22:23], v[22:23], v[28:29]
	v_pk_mul_f32 v[20:21], v[20:21], v[24:25]
	v_pk_mul_f32 v[24:25], v[18:19], v[30:31]
	v_pk_mul_f32 v[18:19], v[16:17], v[26:27]
	v_cvt_pk_bf16_f32 v16, v20, v21
	v_cvt_pk_bf16_f32 v17, v22, v23
	s_nop 0
	v_cvt_pk_bf16_f32 v18, v18, v19
	v_cvt_pk_bf16_f32 v19, v24, v25
	global_load_dwordx4 v[20:23], v[36:37], off offset:2048
	s_nop 0
	global_store_dwordx4 v[34:35], v[16:19], off offset:256
	s_waitcnt vmcnt(1)
	s_nop 0
	v_lshlrev_b32_e32 v16, 16, v20
	v_and_b32_e32 v17, 0xffff0000, v20
	v_lshlrev_b32_e32 v18, 16, v21
	v_and_b32_e32 v19, 0xffff0000, v21
	v_lshlrev_b32_e32 v20, 16, v22
	v_and_b32_e32 v21, 0xffff0000, v22
	v_lshlrev_b32_e32 v22, 16, v23
	v_and_b32_e32 v23, 0xffff0000, v23
	v_max_f32_e32 v16, v16, v16
	v_max_f32_e32 v20, v20, v20
	v_max_f32_e32 v17, v17, v17
	v_max_f32_e32 v21, v21, v21
	v_max_f32_e32 v24, v18, v18
	v_max_f32_e32 v22, v22, v22
	v_max_f32_e32 v25, v19, v19
	v_max_f32_e32 v23, v23, v23
	v_max_f32_e32 v16, 0xda24260, v16
	v_max_f32_e32 v18, 0xda24260, v20
	v_max_f32_e32 v17, 0xda24260, v17
	v_max_f32_e32 v19, 0xda24260, v21
	v_max_f32_e32 v20, 0xda24260, v24
	v_max_f32_e32 v22, 0xda24260, v22
	v_max_f32_e32 v21, 0xda24260, v25
	v_max_f32_e32 v23, 0xda24260, v23
	v_pk_mul_f32 v[14:15], v[14:15], v[20:21]
	v_pk_mul_f32 v[12:13], v[12:13], v[16:17]
	v_pk_mul_f32 v[16:17], v[10:11], v[22:23]
	v_pk_mul_f32 v[10:11], v[8:9], v[18:19]
	v_cvt_pk_bf16_f32 v8, v12, v13
	v_cvt_pk_bf16_f32 v9, v14, v15
	s_nop 0
	v_cvt_pk_bf16_f32 v10, v10, v11
	v_cvt_pk_bf16_f32 v11, v16, v17
	global_load_dwordx4 v[12:15], v[36:37], off offset:2304
	v_lshlrev_b64 v[16:17], 11, v[32:33]
	v_lshl_add_u64 v[16:17], s[6:7], 0, v[16:17]
	v_lshl_add_u64 v[16:17], v[16:17], 0, v[152:153]
	global_store_dwordx4 v[16:17], v[8:11], off
	s_waitcnt vmcnt(1)
	s_nop 0
	v_lshlrev_b32_e32 v8, 16, v12
	v_and_b32_e32 v9, 0xffff0000, v12
	v_lshlrev_b32_e32 v10, 16, v13
	v_and_b32_e32 v11, 0xffff0000, v13
	v_lshlrev_b32_e32 v12, 16, v14
	v_and_b32_e32 v13, 0xffff0000, v14
	v_lshlrev_b32_e32 v14, 16, v15
	v_and_b32_e32 v15, 0xffff0000, v15
	v_max_f32_e32 v8, v8, v8
	v_max_f32_e32 v12, v12, v12
	v_max_f32_e32 v9, v9, v9
	v_max_f32_e32 v13, v13, v13
	v_max_f32_e32 v14, v14, v14
	v_max_f32_e32 v15, v15, v15
	v_max_f32_e32 v18, v10, v10
	v_max_f32_e32 v19, v11, v11
	v_max_f32_e32 v8, 0xda24260, v8
	v_max_f32_e32 v10, 0xda24260, v12
	v_max_f32_e32 v9, 0xda24260, v9
	v_max_f32_e32 v11, 0xda24260, v13
	v_max_f32_e32 v14, 0xda24260, v14
	v_max_f32_e32 v15, 0xda24260, v15
	v_max_f32_e32 v12, 0xda24260, v18
	v_max_f32_e32 v13, 0xda24260, v19
	v_pk_mul_f32 v[4:5], v[4:5], v[8:9]
	v_pk_mul_f32 v[8:9], v[2:3], v[14:15]
	v_pk_mul_f32 v[2:3], v[0:1], v[10:11]
	v_pk_mul_f32 v[6:7], v[6:7], v[12:13]
	v_cvt_pk_bf16_f32 v0, v4, v5
	s_nop 0
	v_cvt_pk_bf16_f32 v1, v6, v7
	v_cvt_pk_bf16_f32 v2, v2, v3
	v_cvt_pk_bf16_f32 v3, v8, v9
	global_store_dwordx4 v[16:17], v[0:3], off offset:256
	s_cbranch_vccnz .LBB0_662
	s_andn2_b64 vcc, exec, s[0:1]
	s_cbranch_vccnz .LBB0_661
	s_barrier
	s_branch .LBB0_661
;     __device__ __forceinline__ void mid(f32x4 (&acc)[2][2][4][2], const pg8::Unit& u, int wr, int wc, int fr, int fq) const {
; #pragma unroll
;         for (int ai = 0; ai < 2; ++ai)
; #pragma unroll
;             for (int m = 0; m < 4; ++m) { const int row = u.pm * 256 + ai * 128 + wr * 64 + m * 16 + fr;
; #pragma unroll
;                 for (int bj = 0; bj < 2; ++bj) { const int col = u.pn * 256 + bj * 128 + wc * 32 + 8 * fq; const bf16_t* gp = G + (size_t)row * 2048 + col;
;                     f32x4 l0, l1, a0, a1; unpack_bf16x8(*(const u32x4*)gp, l0, l1); unpack_bf16x8(*(const u32x4*)(gp + 1024), a0, a1);
; #pragma unroll
;                     for (int i = 0; i < 4; ++i) { acc[ai][bj][m][0][i] *= l0[i] * __builtin_amdgcn_rcpf(fmaxf(a0[i], 1e-30f)); acc[ai][bj][m][1][i] *= l1[i] * __builtin_amdgcn_rcpf(fmaxf(a1[i], 1e-30f)); } } }
.LBB0_674:
	s_waitcnt vmcnt(0)
	v_readlane_b32 s46, v254, 22
	s_barrier
	s_and_b32 s0, s44, 7
	s_lshr_b32 s1, s44, 3
	s_and_b32 s1, s1, 7
	s_lshl_b32 s0, s0, 3
	s_add_i32 s0, s0, s1
	s_mulk_i32 s0, 0x110
	s_addk_i32 s0, 0x100
	s_lshr_b32 s1, s44, 6
	v_readlane_b32 s2, v254, 21
	s_nop 3
	s_lshl_b32 s3, s1, 8
	s_lshl_b32 s2, s2, 5
	s_add_i32 s3, s3, s2
	s_mov_b32 s4, 0x1000
	s_add_u32 s8, s88, 0x14000000
	s_addc_u32 s9, s89, 0
	s_add_u32 s10, s88, 0x1600000
	s_addc_u32 s11, s89, 0
	s_mov_b64 s[6:7], 0x4000
	s_mov_b64 s[12:13], 0x200
	v_and_b32_e32 v8, 15, v132
	v_lshrrev_b32_e32 v9, 4, v132
	v_add_u32_e32 v5, s0, v8
	v_lshrrev_b32_e32 v6, 2, v8
	v_and_b32_e32 v7, 3, v8
	v_lshl_add_u32 v6, v6, 3, v7
	v_add_u32_e32 v6, s3, v6
	v_lshlrev_b32_e32 v7, 4, v9
	v_mul_lo_u32 v10, v5, s4
	v_mul_lo_u32 v12, v6, s4
	v_mov_b32_e32 v11, 0
	v_mov_b32_e32 v13, 0
	v_add_u32_e32 v10, v10, v7
	v_add_u32_e32 v12, v12, v7
	v_lshl_add_u64 v[10:11], s[8:9], 0, v[10:11]
	v_lshl_add_u64 v[12:13], s[10:11], 0, v[12:13]
	v_lshl_add_u64 v[14:15], v[12:13], 0, s[6:7]
	v_lshl_add_u32 v2, v9, 3, s3
	s_add_u32 s20, s88, 0xfc00000
	s_addc_u32 s21, s89, 0
	v_lshlrev_b32_e32 v0, 12, v5
	v_lshl_add_u32 v0, v2, 1, v0
	v_mov_b32_e32 v1, 0
	v_lshl_add_u64 v[0:1], s[20:21], 0, v[0:1]
	global_load_dwordx4 v[120:123], v[0:1], off
	global_load_dwordx4 v[124:127], v[0:1], off offset:2048
	v_mov_b32_e32 v16, 0
	v_mov_b32_e32 v17, 0
	v_mov_b32_e32 v18, 0
	v_mov_b32_e32 v19, 0
	v_mov_b32_e32 v20, 0
	v_mov_b32_e32 v21, 0
	v_mov_b32_e32 v22, 0
	v_mov_b32_e32 v23, 0
	global_load_dwordx4 v[24:27], v[10:11], off
	global_load_dwordx4 v[28:31], v[12:13], off
	global_load_dwordx4 v[32:35], v[14:15], off
	global_load_dwordx4 v[36:39], v[10:11], off offset:64
	global_load_dwordx4 v[40:43], v[12:13], off offset:64
	global_load_dwordx4 v[44:47], v[14:15], off offset:64
	global_load_dwordx4 v[48:51], v[10:11], off offset:128
	global_load_dwordx4 v[52:55], v[12:13], off offset:128
	global_load_dwordx4 v[56:59], v[14:15], off offset:128
	global_load_dwordx4 v[60:63], v[10:11], off offset:192
	global_load_dwordx4 v[64:67], v[12:13], off offset:192
	global_load_dwordx4 v[68:71], v[14:15], off offset:192
	global_load_dwordx4 v[72:75], v[10:11], off offset:256
	global_load_dwordx4 v[76:79], v[12:13], off offset:256
	global_load_dwordx4 v[80:83], v[14:15], off offset:256
	global_load_dwordx4 v[84:87], v[10:11], off offset:320
	global_load_dwordx4 v[88:91], v[12:13], off offset:320
	global_load_dwordx4 v[92:95], v[14:15], off offset:320
	global_load_dwordx4 v[96:99], v[10:11], off offset:384
	global_load_dwordx4 v[100:103], v[12:13], off offset:384
	global_load_dwordx4 v[104:107], v[14:15], off offset:384
	global_load_dwordx4 v[108:111], v[10:11], off offset:448
	global_load_dwordx4 v[112:115], v[12:13], off offset:448
	global_load_dwordx4 v[116:119], v[14:15], off offset:448
	s_mov_b32 s5, 4
.Lstrip_P3_k1:
	s_waitcnt vmcnt(21)
	v_mfma_f32_16x16x32_bf16 v[16:19], v[28:31], v[24:27], v[16:19]
	v_mfma_f32_16x16x32_bf16 v[20:23], v[32:35], v[24:27], v[20:23]
	global_load_dwordx4 v[24:27], v[10:11], off offset:512
	global_load_dwordx4 v[28:31], v[12:13], off offset:512
	global_load_dwordx4 v[32:35], v[14:15], off offset:512
	s_waitcnt vmcnt(21)
	v_mfma_f32_16x16x32_bf16 v[16:19], v[40:43], v[36:39], v[16:19]
	v_mfma_f32_16x16x32_bf16 v[20:23], v[44:47], v[36:39], v[20:23]
	global_load_dwordx4 v[36:39], v[10:11], off offset:576
	global_load_dwordx4 v[40:43], v[12:13], off offset:576
	global_load_dwordx4 v[44:47], v[14:15], off offset:576
	s_waitcnt vmcnt(21)
	v_mfma_f32_16x16x32_bf16 v[16:19], v[52:55], v[48:51], v[16:19]
	v_mfma_f32_16x16x32_bf16 v[20:23], v[56:59], v[48:51], v[20:23]
	global_load_dwordx4 v[48:51], v[10:11], off offset:640
	global_load_dwordx4 v[52:55], v[12:13], off offset:640
	global_load_dwordx4 v[56:59], v[14:15], off offset:640
	s_waitcnt vmcnt(21)
	v_mfma_f32_16x16x32_bf16 v[16:19], v[64:67], v[60:63], v[16:19]
	v_mfma_f32_16x16x32_bf16 v[20:23], v[68:71], v[60:63], v[20:23]
	global_load_dwordx4 v[60:63], v[10:11], off offset:704
	global_load_dwordx4 v[64:67], v[12:13], off offset:704
	global_load_dwordx4 v[68:71], v[14:15], off offset:704
	s_waitcnt vmcnt(21)
	v_mfma_f32_16x16x32_bf16 v[16:19], v[76:79], v[72:75], v[16:19]
	v_mfma_f32_16x16x32_bf16 v[20:23], v[80:83], v[72:75], v[20:23]
	global_load_dwordx4 v[72:75], v[10:11], off offset:768
	global_load_dwordx4 v[76:79], v[12:13], off offset:768
	global_load_dwordx4 v[80:83], v[14:15], off offset:768
	s_waitcnt vmcnt(21)
	v_mfma_f32_16x16x32_bf16 v[16:19], v[88:91], v[84:87], v[16:19]
	v_mfma_f32_16x16x32_bf16 v[20:23], v[92:95], v[84:87], v[20:23]
	global_load_dwordx4 v[84:87], v[10:11], off offset:832
	global_load_dwordx4 v[88:91], v[12:13], off offset:832
	global_load_dwordx4 v[92:95], v[14:15], off offset:832
	s_waitcnt vmcnt(21)
	v_mfma_f32_16x16x32_bf16 v[16:19], v[100:103], v[96:99], v[16:19]
	v_mfma_f32_16x16x32_bf16 v[20:23], v[104:107], v[96:99], v[20:23]
	global_load_dwordx4 v[96:99], v[10:11], off offset:896
	global_load_dwordx4 v[100:103], v[12:13], off offset:896
	global_load_dwordx4 v[104:107], v[14:15], off offset:896
	s_waitcnt vmcnt(21)
	v_mfma_f32_16x16x32_bf16 v[16:19], v[112:115], v[108:111], v[16:19]
	v_mfma_f32_16x16x32_bf16 v[20:23], v[116:119], v[108:111], v[20:23]
	global_load_dwordx4 v[108:111], v[10:11], off offset:960
	global_load_dwordx4 v[112:115], v[12:13], off offset:960
	global_load_dwordx4 v[116:119], v[14:15], off offset:960
	v_lshl_add_u64 v[10:11], v[10:11], 0, s[12:13]
	v_lshl_add_u64 v[12:13], v[12:13], 0, s[12:13]
	v_lshl_add_u64 v[14:15], v[14:15], 0, s[12:13]
	s_add_i32 s5, s5, -1
	s_cmp_lg_u32 s5, 0
	s_cbranch_scc1 .Lstrip_P3_k1
; __device__ __forceinline__ u32x4 pack8(f32x4 a, f32x4 b) { u32x4 w; w.x = cvt_pk_bf16(a[0], a[1]); w.y = cvt_pk_bf16(a[2], a[3]); w.z = cvt_pk_bf16(b[0], b[1]); w.w = cvt_pk_bf16(b[2], b[3]); return w; }
; #define EPI_LOOP(...) _Pragma("unroll") for (int ai = 0; ai < 2; ++ai) _Pragma("unroll") for (int m = 0; m < 4; ++m) { const int row = u.pm * 256 + ai * 128 + wr * 64 + m * 16 + fr; \
;     _Pragma("unroll") for (int bj = 0; bj < 2; ++bj) { const int tc = bj * 128 + wc * 32 + 8 * fq; f32x4 v0 = acc[ai][bj][m][0], v1 = acc[ai][bj][m][1]; __VA_ARGS__ } }
;     __device__ __forceinline__ void mid(f32x4 (&acc)[2][2][4][2], const pg8::Unit& u, int wr, int wc, int fr, int fq) const {
; #pragma unroll
;         for (int ai = 0; ai < 2; ++ai)
; #pragma unroll
;             for (int m = 0; m < 4; ++m) { const int row = u.pm * 256 + ai * 128 + wr * 64 + m * 16 + fr;
; #pragma unroll
;                 for (int bj = 0; bj < 2; ++bj) { const int col = u.pn * 256 + bj * 128 + wc * 32 + 8 * fq; const bf16_t* gp = G + (size_t)row * 2048 + col;
;                     f32x4 l0, l1, a0, a1; unpack_bf16x8(*(const u32x4*)gp, l0, l1); unpack_bf16x8(*(const u32x4*)(gp + 1024), a0, a1);
; #pragma unroll
;                     for (int i = 0; i < 4; ++i) { acc[ai][bj][m][0][i] *= l0[i] * __builtin_amdgcn_rcpf(fmaxf(a0[i], 1e-30f)); acc[ai][bj][m][1][i] *= l1[i] * __builtin_amdgcn_rcpf(fmaxf(a1[i], 1e-30f)); } } }
;     }
;     __device__ __forceinline__ void operator()(const f32x4 (&acc)[2][2][4][2], const pg8::Unit& u, int wr, int wc, int fr, int fq) const {
;         EPI_LOOP({ const int col = u.pn * 256 + tc; f32x4 a0, a1; unpack_bf16x8(*(const u32x4*)(G + (size_t)row * 2048 + 1024 + col), a0, a1);
;                    _Pragma("unroll") for (int i = 0; i < 4; ++i) { a0[i] = fmaxf(a0[i], 1e-30f); a1[i] = fmaxf(a1[i], 1e-30f); }
;                    *(u32x4*)(MIXED + (size_t)row * D + col) = pack8(v0 * a0, v1 * a1); })
;     }
	s_nop 7
	s_nop 1
	v_lshlrev_b32_e32 v136, 16, v120
	v_and_b32_e32 v137, 0xffff0000, v120
	v_lshlrev_b32_e32 v138, 16, v121
	v_and_b32_e32 v139, 0xffff0000, v121
	v_lshlrev_b32_e32 v140, 16, v122
	v_and_b32_e32 v141, 0xffff0000, v122
	v_lshlrev_b32_e32 v142, 16, v123
	v_and_b32_e32 v143, 0xffff0000, v123
	v_lshlrev_b32_e32 v144, 16, v124
	v_and_b32_e32 v145, 0xffff0000, v124
	v_lshlrev_b32_e32 v146, 16, v125
	v_and_b32_e32 v147, 0xffff0000, v125
	v_lshlrev_b32_e32 v148, 16, v126
	v_and_b32_e32 v149, 0xffff0000, v126
	v_lshlrev_b32_e32 v150, 16, v127
	v_and_b32_e32 v151, 0xffff0000, v127
	v_max_f32_e32 v144, 0xda24260, v144
	v_max_f32_e32 v145, 0xda24260, v145
	v_max_f32_e32 v146, 0xda24260, v146
	v_max_f32_e32 v147, 0xda24260, v147
	v_max_f32_e32 v148, 0xda24260, v148
	v_max_f32_e32 v149, 0xda24260, v149
	v_max_f32_e32 v150, 0xda24260, v150
	v_max_f32_e32 v151, 0xda24260, v151
	v_rcp_f32_e32 v152, v144
	v_rcp_f32_e32 v153, v145
	v_rcp_f32_e32 v154, v146
	v_rcp_f32_e32 v155, v147
	v_rcp_f32_e32 v156, v148
	v_rcp_f32_e32 v157, v149
	v_rcp_f32_e32 v158, v150
	v_rcp_f32_e32 v159, v151
	s_nop 0
	v_mul_f32_e32 v136, v152, v136
	v_mul_f32_e32 v137, v153, v137
	v_mul_f32_e32 v138, v154, v138
	v_mul_f32_e32 v139, v155, v139
	v_mul_f32_e32 v140, v156, v140
	v_mul_f32_e32 v141, v157, v141
	v_mul_f32_e32 v142, v158, v142
	v_mul_f32_e32 v143, v159, v143
	v_mul_f32_e32 v16, v16, v136
	v_mul_f32_e32 v17, v17, v137
	v_mul_f32_e32 v18, v18, v138
	v_mul_f32_e32 v19, v19, v139
	v_mul_f32_e32 v20, v20, v140
	v_mul_f32_e32 v21, v21, v141
	v_mul_f32_e32 v22, v22, v142
	v_mul_f32_e32 v23, v23, v143
	s_nop 1
	s_mov_b32 s5, 3
.Lstrip_P3_k2:
	s_waitcnt vmcnt(21)
	v_mfma_f32_16x16x32_bf16 v[16:19], v[28:31], v[24:27], v[16:19]
	v_mfma_f32_16x16x32_bf16 v[20:23], v[32:35], v[24:27], v[20:23]
	global_load_dwordx4 v[24:27], v[10:11], off offset:512
	global_load_dwordx4 v[28:31], v[12:13], off offset:512
	global_load_dwordx4 v[32:35], v[14:15], off offset:512
	s_waitcnt vmcnt(21)
	v_mfma_f32_16x16x32_bf16 v[16:19], v[40:43], v[36:39], v[16:19]
	v_mfma_f32_16x16x32_bf16 v[20:23], v[44:47], v[36:39], v[20:23]
	global_load_dwordx4 v[36:39], v[10:11], off offset:576
	global_load_dwordx4 v[40:43], v[12:13], off offset:576
	global_load_dwordx4 v[44:47], v[14:15], off offset:576
	s_waitcnt vmcnt(21)
	v_mfma_f32_16x16x32_bf16 v[16:19], v[52:55], v[48:51], v[16:19]
	v_mfma_f32_16x16x32_bf16 v[20:23], v[56:59], v[48:51], v[20:23]
	global_load_dwordx4 v[48:51], v[10:11], off offset:640
	global_load_dwordx4 v[52:55], v[12:13], off offset:640
	global_load_dwordx4 v[56:59], v[14:15], off offset:640
	s_waitcnt vmcnt(21)
	v_mfma_f32_16x16x32_bf16 v[16:19], v[64:67], v[60:63], v[16:19]
	v_mfma_f32_16x16x32_bf16 v[20:23], v[68:71], v[60:63], v[20:23]
	global_load_dwordx4 v[60:63], v[10:11], off offset:704
	global_load_dwordx4 v[64:67], v[12:13], off offset:704
	global_load_dwordx4 v[68:71], v[14:15], off offset:704
	s_waitcnt vmcnt(21)
	v_mfma_f32_16x16x32_bf16 v[16:19], v[76:79], v[72:75], v[16:19]
	v_mfma_f32_16x16x32_bf16 v[20:23], v[80:83], v[72:75], v[20:23]
	global_load_dwordx4 v[72:75], v[10:11], off offset:768
	global_load_dwordx4 v[76:79], v[12:13], off offset:768
	global_load_dwordx4 v[80:83], v[14:15], off offset:768
	s_waitcnt vmcnt(21)
	v_mfma_f32_16x16x32_bf16 v[16:19], v[88:91], v[84:87], v[16:19]
	v_mfma_f32_16x16x32_bf16 v[20:23], v[92:95], v[84:87], v[20:23]
	global_load_dwordx4 v[84:87], v[10:11], off offset:832
	global_load_dwordx4 v[88:91], v[12:13], off offset:832
	global_load_dwordx4 v[92:95], v[14:15], off offset:832
	s_waitcnt vmcnt(21)
	v_mfma_f32_16x16x32_bf16 v[16:19], v[100:103], v[96:99], v[16:19]
	v_mfma_f32_16x16x32_bf16 v[20:23], v[104:107], v[96:99], v[20:23]
	global_load_dwordx4 v[96:99], v[10:11], off offset:896
	global_load_dwordx4 v[100:103], v[12:13], off offset:896
	global_load_dwordx4 v[104:107], v[14:15], off offset:896
	s_waitcnt vmcnt(21)
	v_mfma_f32_16x16x32_bf16 v[16:19], v[112:115], v[108:111], v[16:19]
	v_mfma_f32_16x16x32_bf16 v[20:23], v[116:119], v[108:111], v[20:23]
	global_load_dwordx4 v[108:111], v[10:11], off offset:960
	global_load_dwordx4 v[112:115], v[12:13], off offset:960
	global_load_dwordx4 v[116:119], v[14:15], off offset:960
	v_lshl_add_u64 v[10:11], v[10:11], 0, s[12:13]
	v_lshl_add_u64 v[12:13], v[12:13], 0, s[12:13]
	v_lshl_add_u64 v[14:15], v[14:15], 0, s[12:13]
	s_add_i32 s5, s5, -1
	s_cmp_lg_u32 s5, 0
	s_cbranch_scc1 .Lstrip_P3_k2
	s_waitcnt vmcnt(21)
	v_mfma_f32_16x16x32_bf16 v[16:19], v[28:31], v[24:27], v[16:19]
	v_mfma_f32_16x16x32_bf16 v[20:23], v[32:35], v[24:27], v[20:23]
	s_waitcnt vmcnt(18)
	v_mfma_f32_16x16x32_bf16 v[16:19], v[40:43], v[36:39], v[16:19]
	v_mfma_f32_16x16x32_bf16 v[20:23], v[44:47], v[36:39], v[20:23]
	s_waitcnt vmcnt(15)
	v_mfma_f32_16x16x32_bf16 v[16:19], v[52:55], v[48:51], v[16:19]
	v_mfma_f32_16x16x32_bf16 v[20:23], v[56:59], v[48:51], v[20:23]
	s_waitcnt vmcnt(12)
	v_mfma_f32_16x16x32_bf16 v[16:19], v[64:67], v[60:63], v[16:19]
	v_mfma_f32_16x16x32_bf16 v[20:23], v[68:71], v[60:63], v[20:23]
	s_waitcnt vmcnt(9)
	v_mfma_f32_16x16x32_bf16 v[16:19], v[76:79], v[72:75], v[16:19]
	v_mfma_f32_16x16x32_bf16 v[20:23], v[80:83], v[72:75], v[20:23]
	s_waitcnt vmcnt(6)
	v_mfma_f32_16x16x32_bf16 v[16:19], v[88:91], v[84:87], v[16:19]
	v_mfma_f32_16x16x32_bf16 v[20:23], v[92:95], v[84:87], v[20:23]
	s_waitcnt vmcnt(3)
	v_mfma_f32_16x16x32_bf16 v[16:19], v[100:103], v[96:99], v[16:19]
	v_mfma_f32_16x16x32_bf16 v[20:23], v[104:107], v[96:99], v[20:23]
	s_waitcnt vmcnt(0)
	v_mfma_f32_16x16x32_bf16 v[16:19], v[112:115], v[108:111], v[16:19]
	v_mfma_f32_16x16x32_bf16 v[20:23], v[116:119], v[108:111], v[20:23]
	s_nop 7
	s_nop 1
	v_mul_f32_e32 v16, v16, v144
	v_mul_f32_e32 v17, v17, v145
	v_mul_f32_e32 v18, v18, v146
	v_mul_f32_e32 v19, v19, v147
	v_mul_f32_e32 v20, v20, v148
	v_mul_f32_e32 v21, v21, v149
	v_mul_f32_e32 v22, v22, v150
	v_mul_f32_e32 v23, v23, v151
	v_cvt_pk_bf16_f32 v136, v16, v17
	v_cvt_pk_bf16_f32 v137, v18, v19
	v_cvt_pk_bf16_f32 v138, v20, v21
	v_cvt_pk_bf16_f32 v139, v22, v23
	s_add_u32 s20, s88, 0x3000000
	s_addc_u32 s21, s89, 0
	v_lshlrev_b32_e32 v0, 11, v5
	v_lshl_add_u32 v0, v2, 1, v0
	v_mov_b32_e32 v1, 0
	v_lshl_add_u64 v[0:1], s[20:21], 0, v[0:1]
	global_store_dwordx4 v[0:1], v[136:139], off

; #define LAS __attribute__((address_space(3)))
;     __device__ bool next(int i, Unit& u) const {
;         const long L = (long)i * G + c; if (L >= nwg) return false;
;         int wgid = (int)L; { const int q = nwg / NXCD, r = nwg % NXCD, xcd = wgid % NXCD, off = wgid / NXCD; wgid = (xcd < r ? xcd * (q + 1) : r * (q + 1) + (xcd - r) * q) + off; }
;         const int nig = WGM * nN, gid = wgid / nig, fm = gid * WGM, gsz = (nM - fm) < WGM ? (nM - fm) : WGM;
;         u.pm = fm + ((wgid % nig) % gsz); u.pn = (wgid % nig) / gsz; return true;
;     }
; __device__ __forceinline__ unsigned cvt_pk_bf16(float lo, float hi) { unsigned r; asm volatile("v_cvt_pk_bf16_f32 %0, %1, %2" : "=v"(r) : "v"(lo), "v"(hi)); return r; }
; template <class Epi>
; __device__ __forceinline__ void gemm_phase(LAS unsigned char* lds, const Gemm g, const StaticOrder& S, const Epi& E) {
;     const int tid = threadIdx.x, wid = __builtin_amdgcn_readfirstlane(tid >> 6), lane = tid & 63, wr = wid >> 2, wc = wid & 3, fr = lane & 15, fq = lane >> 4;
;     const int K = g.K, nt = K / BK;
;     unsigned voffA[2], voffB[2];
; #pragma unroll
;     for (int i = 0; i < 2; ++i) { int R, C; stage_rc(tid * 16 + i * 8192, R, C); const int Rb = (R & ~31) + perm32(R & 31);
;         voffA[i] = (unsigned)(R * K + C) * 2u; voffB[i] = (unsigned)(Rb * K + C) * 2u; }
;     const size_t kstep = (size_t)(BK * 2);
;     const size_t hstep = (size_t)HALF * K * 2;
;     const size_t tstep = 2 * hstep;
;     const unsigned ldsw = (unsigned)wid * 1024u;
;     const int aoff = lds_byte(wr * 64 + fr, fq * 8), boff = lds_byte(wc * 32 + fr, fq * 8);
;     ...
;     Unit cur, nxt; int ui = 0;
;     if (!S.next(0, cur)) return;
;     f32x4 acc[2][2][4][2];
; #pragma unroll
;     for (int a = 0; a < 2; ++a)
; #pragma unroll
;         for (int b = 0; b < 2; ++b)
; #pragma unroll
;             for (int m = 0; m < 4; ++m)
; #pragma unroll
;                 for (int n = 0; n < 2; ++n) acc[a][b][m][n] = (f32x4){0.f, 0.f, 0.f, 0.f};
;     bf16x8 At[4][2], B0[2][2], B1[2][2];
;     const char* cA = (const char*)g.A + (size_t)cur.pm * tstep; const char* cB = (const char*)g.Bt + (size_t)cur.pn * tstep;
;     PG8_STAGE(PG8_SB(0, 0), cB, voffB); PG8_STAGE(PG8_SB(0, 1), cB + hstep, voffB); PG8_STAGE(PG8_SA(0, 0), cA, voffA); PG8_STAGE(PG8_SA(0, 1), cA + hstep, voffA);
;     if (wr == 1) PG8_BAR;
;     PG8_WAIT_V(2); PG8_BAR;
.LBB0_727:
	s_or_b64 exec, exec, s[0:1]
	s_cmp_lt_i32 s90, 5
	s_cselect_b64 s[0:1], -1, 0
	s_cmp_gt_i32 s91, 4
	s_cselect_b64 s[2:3], -1, 0
	s_and_b64 s[0:1], s[0:1], s[2:3]
	s_andn2_b64 vcc, exec, s[0:1]
	s_waitcnt lgkmcnt(0)
	s_barrier
	s_cbranch_vccnz .LBB0_794
	s_cmpk_lt_i32 s44, 0x110
	s_cselect_b64 s[0:1], -1, 0
	s_cmpk_gt_i32 s44, 0x10f
	v_readfirstlane_b32 s2, v134
	s_cbranch_scc1 .LBB0_730
	s_ashr_i32 s3, s44, 31
	s_lshr_b32 s3, s3, 29
	s_add_i32 s3, s44, s3
	s_ashr_i32 s4, s3, 3
	s_and_b32 s3, s3, -8
	s_sub_i32 s3, s44, s3
	s_cmp_lt_i32 s3, 0
	s_cselect_b32 s5, 35, 34
	s_mul_i32 s3, s3, s5
	s_add_i32 s3, s3, s4
	s_ashr_i32 s4, s3, 31
	s_lshr_b32 s4, s4, 27
	s_add_i32 s4, s3, s4
	s_ashr_i32 s4, s4, 5
	s_lshl_b32 s6, s4, 3
	s_sub_i32 s5, 0x44, s6
	s_lshl_b32 s4, s4, 5
	s_min_u32 s7, s5, 8
	s_sub_i32 s3, s3, s4
	s_sext_i32_i8 s4, s3
	v_cvt_f32_ubyte0_e32 v1, s7
	v_cvt_f32_i32_e32 v0, s4
	v_rcp_iflag_f32_e32 v2, v1
	s_ashr_i32 s4, s4, 30
	s_or_b32 s8, s4, 1
	v_mul_f32_e32 v2, v0, v2
	v_trunc_f32_e32 v2, v2
	v_fma_f32 v0, -v2, v1, v0
	v_cvt_i32_f32_e32 v2, v2
	v_cmp_ge_f32_e64 s[4:5], |v0|, v1
	s_and_b64 s[4:5], s[4:5], exec
	s_cselect_b32 s4, s8, 0
	v_readfirstlane_b32 s5, v2
	s_add_i32 s4, s5, s4
	s_sext_i32_i8 s22, s4
	s_mul_i32 s4, s4, s7
	s_sub_i32 s3, s3, s4
	s_sext_i32_i8 s3, s3
	s_add_i32 s24, s6, s3
	s_and_b32 s3, s44, 7
	s_lshr_b32 s4, s44, 3
	s_and_b32 s4, s4, 7
	s_lshl_b32 s3, s3, 3
	s_add_i32 s3, s3, s4
	s_mul_i32 s24, s3, 17
	s_lshr_b32 s22, s44, 6
.LBB0_730:
	s_andn2_b64 vcc, exec, s[0:1]
	s_cbranch_vccnz .LBB0_794
	v_lshrrev_b32_e32 v2, 1, v134
	v_lshrrev_b32_e32 v3, 5, v134
	v_and_b32_e32 v2, 24, v2
	v_and_b32_e32 v3, 4, v3
	v_bfe_u32 v4, v134, 2, 2
	s_add_u32 s33, s88, 0x3000000
	v_lshlrev_b32_e32 v0, 4, v134
	v_and_b32_e32 v1, 32, v134
	v_bfe_u32 v10, v134, 2, 4
	v_or3_b32 v2, v3, v4, v2
	v_lshrrev_b32_e32 v3, 3, v134
	s_movk_i32 s0, 0x70
	s_addc_u32 s34, s89, 0
	v_bitop3_b32 v8, v0, v1, 48 bitop3:0x6c
	v_and_b32_e32 v9, 64, v134
	v_and_or_b32 v4, v3, s0, v10
	s_movk_i32 s0, 0x60
	v_add_u32_e32 v11, 0x2000, v0
	s_add_u32 s35, s88, 0x1a00000
	v_or_b32_e32 v1, v8, v9
	v_and_or_b32 v3, v3, s0, v2
	v_lshrrev_b32_e32 v0, 7, v11
	s_movk_i32 s0, 0xf0
	s_addc_u32 s36, s89, 0
	v_lshl_or_b32 v130, v3, 11, v1
	v_and_or_b32 v3, v0, s0, v10
	s_movk_i32 s0, 0xe0
	s_lshr_b32 s4, s2, 6
	s_ashr_i32 s25, s24, 31
	s_ashr_i32 s23, s22, 31
	s_lshr_b32 s3, s2, 8
	v_and_or_b32 v0, v0, s0, v2
	s_lshl_b32 s37, s4, 10
	s_lshl_b64 s[0:1], s[24:25], 15
	s_lshl_b64 s[6:7], s[22:23], 19
	s_add_u32 s28, s35, s6
	s_addc_u32 s29, s36, s7
	s_add_i32 s38, s37, 0
	s_add_i32 m0, s38, 0x10000
	v_lshl_or_b32 v138, v0, 11, v1
	global_load_lds_dwordx4 v130, s[28:29]
	s_add_i32 m0, s38, 0x12000
	s_add_u32 s6, s28, 0x40000
	global_load_lds_dwordx4 v138, s[28:29]
	s_addc_u32 s7, s29, 0
	s_add_i32 m0, s38, 0x14000
	v_lshl_or_b32 v128, v4, 11, v1
	global_load_lds_dwordx4 v130, s[6:7]
	s_add_i32 m0, s38, 0x16000
	s_add_u32 s26, s33, s0
	s_addc_u32 s27, s34, s1
	s_add_i32 s39, s38, 0x2000
	global_load_lds_dwordx4 v138, s[6:7]
	s_mov_b32 m0, s38
	s_add_u32 s0, s26, 0x40000
	v_lshl_or_b32 v136, v3, 11, v1
	global_load_lds_dwordx4 v128, s[26:27]
	s_mov_b32 m0, s39
	s_addc_u32 s1, s27, 0
	s_add_i32 s40, s38, 0x4000
	global_load_lds_dwordx4 v136, s[26:27]
	s_mov_b32 m0, s40
	s_add_i32 s41, s38, 0x6000
	global_load_lds_dwordx4 v128, s[0:1]
	s_mov_b32 m0, s41
	v_mov_b32_e32 v141, 0
	global_load_lds_dwordx4 v136, s[0:1]
	v_mov_b32_e32 v131, v141
	v_mov_b32_e32 v139, v141
	v_mov_b32_e32 v129, v141
	v_mov_b32_e32 v137, v141
	s_cmp_eq_u32 s3, 1
	s_mov_b32 s42, 0
	v_lshl_add_u64 v[6:7], s[28:29], 0, v[130:131]
	v_lshl_add_u64 v[4:5], s[28:29], 0, v[138:139]
	v_lshl_add_u64 v[0:1], s[26:27], 0, v[128:129]
	s_cselect_b64 s[0:1], -1, 0
	s_cmp_lg_u32 s3, 1
	v_lshl_add_u64 v[2:3], s[26:27], 0, v[136:137]
	s_cbranch_scc1 .LBB0_733
	s_barrier
.LBB0_733:
	s_add_u32 s6, s88, 0x18400000
	s_addc_u32 s7, s89, 0
	s_add_u32 s8, s88, 0x100000
	s_addc_u32 s9, s89, 0
	s_lshl_b32 s4, s4, 5
	s_mov_b64 s[10:11], 0x80
	s_and_b32 s14, s4, 0x60
	s_add_i32 m0, s38, 0x18000
	v_lshl_add_u64 v[6:7], v[6:7], 0, s[10:11]
	s_lshl_b32 s12, s3, 13
	s_lshl_b32 s13, s14, 7
	s_waitcnt vmcnt(2)
	s_barrier
	global_load_lds_dwordx4 v[6:7], off
	v_lshl_add_u64 v[4:5], v[4:5], 0, s[10:11]
	s_add_i32 m0, s38, 0x1a000
	s_add_i32 s43, s38, 0x8000
	s_add_i32 s45, s38, 0xa000
	global_load_lds_dwordx4 v[4:5], off
	v_lshl_add_u64 v[0:1], v[0:1], 0, s[10:11]
	s_mov_b32 m0, s43
	s_add_u32 s4, s28, 0x40080
	global_load_lds_dwordx4 v[0:1], off
	v_lshl_add_u64 v[0:1], v[2:3], 0, s[10:11]
	s_mov_b32 m0, s45
	s_addc_u32 s5, s29, 0
	global_load_lds_dwordx4 v[0:1], off
	s_add_i32 m0, s38, 0x1c000
	v_lshl_add_u64 v[0:1], s[4:5], 0, v[130:131]
	global_load_lds_dwordx4 v[0:1], off
	v_lshl_add_u64 v[0:1], s[4:5], 0, v[138:139]
	s_add_i32 m0, s38, 0x1e000
	v_lshlrev_b32_e32 v3, 2, v134
	global_load_lds_dwordx4 v[0:1], off
	v_and_b32_e32 v0, 15, v134
	v_bfe_u32 v1, v134, 4, 2
	v_lshl_or_b32 v133, s3, 6, v0
	v_lshlrev_b32_e32 v2, 4, v1
	v_lshlrev_b32_e32 v4, 6, v134
	s_movk_i32 s3, 0x3c0
	v_lshl_or_b32 v0, v0, 6, v2
	v_and_b32_e32 v3, 32, v3
	v_and_or_b32 v2, v4, s3, v2
	s_cmpk_lt_u32 s2, 0x100
	v_cmp_eq_u32_e64 s[2:3], 0, v1
	v_lshl_or_b32 v156, v1, 3, s14
	v_lshlrev_b32_e32 v1, 8, v134
	v_bitop3_b32 v135, s13, v2, v3 bitop3:0xf6
	v_and_b32_e32 v1, 0x38000, v1
	v_lshlrev_b32_e32 v2, 11, v10
	v_or3_b32 v1, v8, v1, v2
	v_add_u32_e32 v142, v1, v9
	v_lshlrev_b32_e32 v1, 4, v11
	v_bitop3_b32 v0, v0, s12, v3 bitop3:0xde
	s_waitcnt vmcnt(6)
	v_and_b32_e32 v1, 0x78000, v1
	s_cselect_b64 s[12:13], -1, 0
	v_or3_b32 v1, v8, v1, v2
	s_add_i32 s49, 0, 0x10000
	s_add_i32 s50, 0, 0x14000
	v_add_u32_e32 v159, 0, v0
	v_mbcnt_lo_u32_b32 v0, -1, 0
	s_ashr_i32 s46, s94, 31
	s_mov_b32 s47, s94
	s_ashr_i32 s48, s44, 31
	v_mov_b32_e32 v143, v141
	v_add_u32_e32 v144, v1, v9
	v_mov_b32_e32 v145, v141
	v_mov_b64_e32 v[146:147], 0x100
	v_mov_b64_e32 v[148:149], 0xff
	v_add_u32_e32 v157, s49, v135
	v_add_u32_e32 v158, s50, v135
	s_movk_i32 s51, 0x3fff
	v_mbcnt_hi_u32_b32 v160, -1, v0
	s_barrier
	s_branch .LBB0_736

; __device__ __forceinline__ u32x4 pack8(f32x4 a, f32x4 b) { u32x4 w; w.x = cvt_pk_bf16(a[0], a[1]); w.y = cvt_pk_bf16(a[2], a[3]); w.z = cvt_pk_bf16(b[0], b[1]); w.w = cvt_pk_bf16(b[2], b[3]); return w; }
;     __device__ __forceinline__ void operator()(const f32x4 (&acc)[2][2][4][2], const pg8::Unit& u, int wr, int wc, int fr, int fq) const {
; #pragma unroll
;         for (int ai = 0; ai < 2; ++ai)
; #pragma unroll
;             for (int m = 0; m < 4; ++m) { const int row = u.pm * 256 + ai * 128 + wr * 64 + m * 16 + fr; float ss = 0.f;
;                 const float* xrow = row < MP ? xp + (size_t)row * D : xs + (size_t)(row - MP) * D;
; #pragma unroll
;                 for (int bj = 0; bj < 2; ++bj) { const int col = u.pn * 256 + bj * 128 + wc * 32 + 8 * fq;
;                     f32x4 v0 = acc[ai][bj][m][0] + *(const f32x4*)(xrow + col), v1 = acc[ai][bj][m][1] + *(const f32x4*)(xrow + col + 4);
;                     ss += (v0[0] * v0[0] + v0[1] * v0[1]) + (v0[2] * v0[2] + v0[3] * v0[3]) + (v1[0] * v1[0] + v1[1] * v1[1]) + (v1[2] * v1[2] + v1[3] * v1[3]);
;                     *(u32x4*)(X2B + (size_t)row * D + col) = pack8(v0, v1); }
;                 ss += __shfl_xor(ss, 16); ss += __shfl_xor(ss, 32);
;                 if (fq == 0) atomicAdd(rss + row, ss); }
;     }
.LBB0_742:
	v_lshl_add_u32 v152, s24, 4, v133
	v_cmp_lt_i32_e32 vcc, s51, v152
	s_and_saveexec_b64 s[24:25], vcc
	s_xor_b64 s[24:25], exec, s[24:25]
	v_add_u32_e32 v140, 0xffffc000, v152
	v_lshlrev_b64 v[150:151], 12, v[140:141]
	v_lshl_add_u64 v[154:155], s[54:55], 0, v[150:151]
	v_mov_b32_e32 v153, v141
	s_andn2_saveexec_b64 s[24:25], s[24:25]
	v_ashrrev_i32_e32 v153, 31, v152
	v_lshlrev_b64 v[150:151], 12, v[152:153]
	v_lshl_add_u64 v[154:155], s[52:53], 0, v[150:151]
	s_or_b64 exec, exec, s[24:25]
	v_lshl_or_b32 v150, s22, 8, v156
	v_ashrrev_i32_e32 v151, 31, v150
	v_lshl_add_u64 v[154:155], v[150:151], 2, v[154:155]
	global_load_dwordx4 v[162:165], v[154:155], off
	global_load_dwordx4 v[166:169], v[154:155], off offset:16
	v_lshlrev_b64 v[170:171], 11, v[152:153]
	v_lshl_add_u64 v[170:171], s[6:7], 0, v[170:171]
	v_lshl_add_u64 v[170:171], v[150:151], 1, v[170:171]
	s_waitcnt vmcnt(0)
	v_pk_add_f32 v[126:127], v[126:127], v[164:165]
	v_pk_add_f32 v[172:173], v[124:125], v[162:163]
	v_pk_add_f32 v[168:169], v[122:123], v[168:169]
	v_pk_add_f32 v[166:167], v[120:121], v[166:167]
	v_cvt_pk_bf16_f32 v120, v172, v173
	v_cvt_pk_bf16_f32 v121, v126, v127
	v_mul_f32_e32 v140, v173, v173
	v_cvt_pk_bf16_f32 v122, v166, v167
	v_cvt_pk_bf16_f32 v123, v168, v169
	global_store_dwordx4 v[170:171], v[120:123], off
	global_load_dwordx4 v[122:125], v[154:155], off offset:512
	s_nop 0
	global_load_dwordx4 v[162:165], v[154:155], off offset:528
	v_mul_f32_e32 v127, v127, v127
	v_and_b32_e32 v121, 64, v160
	v_mul_f32_e32 v154, v167, v167
	v_fmac_f32_e32 v140, v172, v172
	v_fmac_f32_e32 v127, v126, v126
	v_xor_b32_e32 v120, 16, v160
	v_add_u32_e32 v121, 64, v121
	v_mul_f32_e32 v155, v169, v169
	v_fmac_f32_e32 v154, v166, v166
	v_add_f32_e32 v126, v140, v127
	v_cmp_lt_i32_e32 vcc, v120, v121
	v_fmac_f32_e32 v155, v168, v168
	v_add_f32_e32 v126, v126, v154
	v_cndmask_b32_e32 v120, v160, v120, vcc
	v_add_f32_e32 v126, v155, v126
	v_lshlrev_b32_e32 v120, 2, v120
	s_waitcnt vmcnt(1)
	v_pk_add_f32 v[118:119], v[118:119], v[124:125]
	v_pk_add_f32 v[116:117], v[116:117], v[122:123]
	s_waitcnt vmcnt(0)
	v_pk_add_f32 v[124:125], v[112:113], v[162:163]
	v_mul_f32_e32 v112, v117, v117
	v_mul_f32_e32 v113, v119, v119
	v_pk_add_f32 v[114:115], v[114:115], v[164:165]
	v_mul_f32_e32 v122, v125, v125
	v_fmac_f32_e32 v112, v116, v116
	v_fmac_f32_e32 v113, v118, v118
	v_mul_f32_e32 v123, v115, v115
	v_fmac_f32_e32 v122, v124, v124
	v_add_f32_e32 v112, v112, v113
	v_fmac_f32_e32 v123, v114, v114
	v_add_f32_e32 v112, v112, v122
	v_add_f32_e32 v112, v123, v112
	v_add_f32_e32 v112, v126, v112
	ds_bpermute_b32 v113, v120, v112
	v_xor_b32_e32 v122, 32, v160
	v_cmp_lt_i32_e32 vcc, v122, v121
	s_waitcnt lgkmcnt(0)
	v_add_f32_e32 v112, v112, v113
	v_cndmask_b32_e32 v121, v160, v122, vcc
	v_cvt_pk_bf16_f32 v122, v116, v117
	v_lshlrev_b32_e32 v116, 2, v121
	ds_bpermute_b32 v113, v116, v112
	v_cvt_pk_bf16_f32 v123, v118, v119
	v_cvt_pk_bf16_f32 v124, v124, v125
	v_cvt_pk_bf16_f32 v125, v114, v115
	global_store_dwordx4 v[170:171], v[122:125], off offset:256
	s_and_saveexec_b64 s[22:23], s[2:3]
	s_cbranch_execz .LBB0_748
	v_lshl_add_u64 v[114:115], v[152:153], 2, s[8:9]
	s_waitcnt lgkmcnt(0)
	v_add_f32_e32 v112, v112, v113
	global_atomic_add_f32 v[114:115], v112, off
.LBB0_748:
	s_or_b64 exec, exec, s[22:23]
	s_waitcnt lgkmcnt(0)
	v_add_u32_e32 v112, 16, v152
	v_cmp_lt_i32_e32 vcc, s51, v112
	s_and_saveexec_b64 s[22:23], vcc
	s_xor_b64 s[22:23], exec, s[22:23]
	v_add_u32_e32 v140, 0xffffc010, v152
	v_lshlrev_b64 v[114:115], 12, v[140:141]
	v_lshl_add_u64 v[114:115], s[54:55], 0, v[114:115]
	v_mov_b32_e32 v113, v141
	s_andn2_saveexec_b64 s[22:23], s[22:23]
	v_ashrrev_i32_e32 v113, 31, v112
	v_lshlrev_b64 v[114:115], 12, v[112:113]
	v_lshl_add_u64 v[114:115], s[52:53], 0, v[114:115]
	s_or_b64 exec, exec, s[22:23]
	v_lshl_add_u64 v[114:115], v[150:151], 2, v[114:115]
	global_load_dwordx4 v[122:125], v[114:115], off
	global_load_dwordx4 v[162:165], v[114:115], off offset:16
	v_lshlrev_b64 v[118:119], 11, v[112:113]
	v_lshl_add_u64 v[118:119], s[6:7], 0, v[118:119]
	v_lshl_add_u64 v[118:119], v[150:151], 1, v[118:119]
	s_waitcnt vmcnt(1)
	v_pk_add_f32 v[124:125], v[110:111], v[124:125]
	v_pk_add_f32 v[122:123], v[108:109], v[122:123]
	s_waitcnt vmcnt(0)
	v_pk_add_f32 v[126:127], v[106:107], v[164:165]
	v_pk_add_f32 v[154:155], v[104:105], v[162:163]
	v_cvt_pk_bf16_f32 v104, v122, v123
	v_cvt_pk_bf16_f32 v105, v124, v125
	v_mul_f32_e32 v121, v127, v127
	v_cvt_pk_bf16_f32 v106, v154, v155
	v_cvt_pk_bf16_f32 v107, v126, v127
	global_store_dwordx4 v[118:119], v[104:107], off
	global_load_dwordx4 v[104:107], v[114:115], off offset:512
	s_nop 0
	global_load_dwordx4 v[108:111], v[114:115], off offset:528
	v_mul_f32_e32 v114, v123, v123
	v_mul_f32_e32 v115, v125, v125
	v_mul_f32_e32 v117, v155, v155
	v_fmac_f32_e32 v114, v122, v122
	v_fmac_f32_e32 v115, v124, v124
	v_fmac_f32_e32 v117, v154, v154
	v_add_f32_e32 v114, v114, v115
	v_fmac_f32_e32 v121, v126, v126
	v_add_f32_e32 v114, v114, v117
	v_add_f32_e32 v114, v121, v114
	s_waitcnt vmcnt(1)
	v_pk_add_f32 v[102:103], v[102:103], v[106:107]
	v_pk_add_f32 v[100:101], v[100:101], v[104:105]
	s_waitcnt vmcnt(0)
	v_pk_add_f32 v[106:107], v[96:97], v[108:109]
	v_mul_f32_e32 v96, v101, v101
	v_mul_f32_e32 v97, v103, v103
	v_pk_add_f32 v[104:105], v[98:99], v[110:111]
	v_mul_f32_e32 v98, v107, v107
	v_fmac_f32_e32 v96, v100, v100
	v_fmac_f32_e32 v97, v102, v102
	v_mul_f32_e32 v99, v105, v105
	v_fmac_f32_e32 v98, v106, v106
	v_add_f32_e32 v96, v96, v97
	v_add_f32_e32 v96, v96, v98
	v_fmac_f32_e32 v99, v104, v104
	v_add_f32_e32 v96, v99, v96
	v_add_f32_e32 v96, v114, v96
	ds_bpermute_b32 v97, v120, v96
	v_cvt_pk_bf16_f32 v98, v100, v101
	v_cvt_pk_bf16_f32 v99, v102, v103
	v_cvt_pk_bf16_f32 v100, v106, v107
	v_cvt_pk_bf16_f32 v101, v104, v105
	s_waitcnt lgkmcnt(0)
	v_add_f32_e32 v96, v96, v97
	ds_bpermute_b32 v97, v116, v96
	global_store_dwordx4 v[118:119], v[98:101], off offset:256
	s_and_saveexec_b64 s[22:23], s[2:3]
	s_cbranch_execz .LBB0_754
	v_lshl_add_u64 v[98:99], v[112:113], 2, s[8:9]
	s_waitcnt lgkmcnt(0)
	v_add_f32_e32 v96, v96, v97
	global_atomic_add_f32 v[98:99], v96, off
; __device__ __forceinline__ u32x4 pack8(f32x4 a, f32x4 b) { u32x4 w; w.x = cvt_pk_bf16(a[0], a[1]); w.y = cvt_pk_bf16(a[2], a[3]); w.z = cvt_pk_bf16(b[0], b[1]); w.w = cvt_pk_bf16(b[2], b[3]); return w; }
;     __device__ __forceinline__ void operator()(const f32x4 (&acc)[2][2][4][2], const pg8::Unit& u, int wr, int wc, int fr, int fq) const {
; #pragma unroll
;         for (int ai = 0; ai < 2; ++ai)
; #pragma unroll
;             for (int m = 0; m < 4; ++m) { const int row = u.pm * 256 + ai * 128 + wr * 64 + m * 16 + fr; float ss = 0.f;
;                 const float* xrow = row < MP ? xp + (size_t)row * D : xs + (size_t)(row - MP) * D;
; #pragma unroll
;                 for (int bj = 0; bj < 2; ++bj) { const int col = u.pn * 256 + bj * 128 + wc * 32 + 8 * fq;
;                     f32x4 v0 = acc[ai][bj][m][0] + *(const f32x4*)(xrow + col), v1 = acc[ai][bj][m][1] + *(const f32x4*)(xrow + col + 4);
;                     ss += (v0[0] * v0[0] + v0[1] * v0[1]) + (v0[2] * v0[2] + v0[3] * v0[3]) + (v1[0] * v1[0] + v1[1] * v1[1]) + (v1[2] * v1[2] + v1[3] * v1[3]);
;                     *(u32x4*)(X2B + (size_t)row * D + col) = pack8(v0, v1); }
;                 ss += __shfl_xor(ss, 16); ss += __shfl_xor(ss, 32);
;                 if (fq == 0) atomicAdd(rss + row, ss); }
;     }
.LBB0_754:
	s_or_b64 exec, exec, s[22:23]
	s_waitcnt lgkmcnt(0)
	v_add_u32_e32 v96, 32, v152
	v_cmp_lt_i32_e32 vcc, s51, v96
	s_and_saveexec_b64 s[22:23], vcc
	s_xor_b64 s[22:23], exec, s[22:23]
	v_add_u32_e32 v140, 0xffffc020, v152
	v_lshlrev_b64 v[98:99], 12, v[140:141]
	v_lshl_add_u64 v[98:99], s[54:55], 0, v[98:99]
	v_mov_b32_e32 v97, v141
	s_andn2_saveexec_b64 s[22:23], s[22:23]
	v_ashrrev_i32_e32 v97, 31, v96
	v_lshlrev_b64 v[98:99], 12, v[96:97]
	v_lshl_add_u64 v[98:99], s[52:53], 0, v[98:99]
	s_or_b64 exec, exec, s[22:23]
	v_lshl_add_u64 v[106:107], v[150:151], 2, v[98:99]
	global_load_dwordx4 v[98:101], v[106:107], off
	global_load_dwordx4 v[102:105], v[106:107], off offset:16
	v_lshlrev_b64 v[108:109], 11, v[96:97]
	v_lshl_add_u64 v[108:109], s[6:7], 0, v[108:109]
	v_lshl_add_u64 v[108:109], v[150:151], 1, v[108:109]
	s_waitcnt vmcnt(1)
	v_pk_add_f32 v[100:101], v[94:95], v[100:101]
	v_pk_add_f32 v[98:99], v[92:93], v[98:99]
	s_waitcnt vmcnt(0)
	v_pk_add_f32 v[104:105], v[90:91], v[104:105]
	v_pk_add_f32 v[102:103], v[88:89], v[102:103]
	v_cvt_pk_bf16_f32 v88, v98, v99
	v_cvt_pk_bf16_f32 v89, v100, v101
	v_mul_f32_e32 v99, v99, v99
	v_cvt_pk_bf16_f32 v90, v102, v103
	v_cvt_pk_bf16_f32 v91, v104, v105
	global_store_dwordx4 v[108:109], v[88:91], off
	global_load_dwordx4 v[88:91], v[106:107], off offset:512
	s_nop 0
	global_load_dwordx4 v[92:95], v[106:107], off offset:528
	v_mul_f32_e32 v101, v101, v101
	v_mul_f32_e32 v103, v103, v103
	v_fmac_f32_e32 v99, v98, v98
	v_fmac_f32_e32 v101, v100, v100
	v_mul_f32_e32 v105, v105, v105
	v_fmac_f32_e32 v103, v102, v102
	v_add_f32_e32 v98, v99, v101
	v_fmac_f32_e32 v105, v104, v104
	v_add_f32_e32 v98, v98, v103
	v_add_f32_e32 v98, v105, v98
	s_waitcnt vmcnt(1)
	v_pk_add_f32 v[86:87], v[86:87], v[90:91]
	v_pk_add_f32 v[84:85], v[84:85], v[88:89]
	s_waitcnt vmcnt(0)
	v_pk_add_f32 v[90:91], v[80:81], v[92:93]
	v_mul_f32_e32 v80, v85, v85
	v_mul_f32_e32 v81, v87, v87
	v_pk_add_f32 v[88:89], v[82:83], v[94:95]
	v_mul_f32_e32 v82, v91, v91
	v_fmac_f32_e32 v80, v84, v84
	v_fmac_f32_e32 v81, v86, v86
	v_mul_f32_e32 v83, v89, v89
	v_fmac_f32_e32 v82, v90, v90
	v_add_f32_e32 v80, v80, v81
	v_add_f32_e32 v80, v80, v82
	v_fmac_f32_e32 v83, v88, v88
	v_add_f32_e32 v80, v83, v80
	v_add_f32_e32 v80, v98, v80
	ds_bpermute_b32 v81, v120, v80
	v_cvt_pk_bf16_f32 v82, v84, v85
	v_cvt_pk_bf16_f32 v83, v86, v87
	v_cvt_pk_bf16_f32 v84, v90, v91
	v_cvt_pk_bf16_f32 v85, v88, v89
	s_waitcnt lgkmcnt(0)
	v_add_f32_e32 v80, v80, v81
	ds_bpermute_b32 v81, v116, v80
	global_store_dwordx4 v[108:109], v[82:85], off offset:256
	s_and_saveexec_b64 s[22:23], s[2:3]
	s_cbranch_execz .LBB0_760
	v_lshl_add_u64 v[82:83], v[96:97], 2, s[8:9]
	s_waitcnt lgkmcnt(0)
	v_add_f32_e32 v80, v80, v81
	global_atomic_add_f32 v[82:83], v80, off
.LBB0_760:
	s_or_b64 exec, exec, s[22:23]
	s_waitcnt lgkmcnt(0)
	v_add_u32_e32 v80, 48, v152
	v_cmp_lt_i32_e32 vcc, s51, v80
	s_and_saveexec_b64 s[22:23], vcc
	s_xor_b64 s[22:23], exec, s[22:23]
	v_add_u32_e32 v140, 0xffffc030, v152
	v_lshlrev_b64 v[82:83], 12, v[140:141]
	v_lshl_add_u64 v[82:83], s[54:55], 0, v[82:83]
	v_mov_b32_e32 v81, v141
	s_andn2_saveexec_b64 s[22:23], s[22:23]
	v_ashrrev_i32_e32 v81, 31, v80
	v_lshlrev_b64 v[82:83], 12, v[80:81]
	v_lshl_add_u64 v[82:83], s[52:53], 0, v[82:83]
	s_or_b64 exec, exec, s[22:23]
	v_lshl_add_u64 v[90:91], v[150:151], 2, v[82:83]
	global_load_dwordx4 v[82:85], v[90:91], off
	global_load_dwordx4 v[86:89], v[90:91], off offset:16
	v_lshlrev_b64 v[92:93], 11, v[80:81]
	v_lshl_add_u64 v[92:93], s[6:7], 0, v[92:93]
	v_lshl_add_u64 v[92:93], v[150:151], 1, v[92:93]
	s_waitcnt vmcnt(1)
	v_pk_add_f32 v[84:85], v[78:79], v[84:85]
	v_pk_add_f32 v[82:83], v[76:77], v[82:83]
	s_waitcnt vmcnt(0)
	v_pk_add_f32 v[88:89], v[74:75], v[88:89]
	v_pk_add_f32 v[86:87], v[72:73], v[86:87]
	v_cvt_pk_bf16_f32 v72, v82, v83
	v_cvt_pk_bf16_f32 v73, v84, v85
	v_mul_f32_e32 v83, v83, v83
	v_cvt_pk_bf16_f32 v74, v86, v87
	v_cvt_pk_bf16_f32 v75, v88, v89
	global_store_dwordx4 v[92:93], v[72:75], off
	global_load_dwordx4 v[72:75], v[90:91], off offset:512
	s_nop 0
	global_load_dwordx4 v[76:79], v[90:91], off offset:528
	v_mul_f32_e32 v85, v85, v85
	v_mul_f32_e32 v87, v87, v87
	v_fmac_f32_e32 v83, v82, v82
	v_fmac_f32_e32 v85, v84, v84
	v_mul_f32_e32 v89, v89, v89
	v_fmac_f32_e32 v87, v86, v86
	v_add_f32_e32 v82, v83, v85
	v_fmac_f32_e32 v89, v88, v88
	v_add_f32_e32 v82, v82, v87
	v_add_f32_e32 v82, v89, v82
	s_waitcnt vmcnt(1)
	v_pk_add_f32 v[70:71], v[70:71], v[74:75]
	v_pk_add_f32 v[68:69], v[68:69], v[72:73]
	s_waitcnt vmcnt(0)
	v_pk_add_f32 v[74:75], v[64:65], v[76:77]
	v_mul_f32_e32 v64, v69, v69
	v_mul_f32_e32 v65, v71, v71
	v_pk_add_f32 v[72:73], v[66:67], v[78:79]
	v_mul_f32_e32 v66, v75, v75
	v_fmac_f32_e32 v64, v68, v68
	v_fmac_f32_e32 v65, v70, v70
	v_mul_f32_e32 v67, v73, v73
	v_fmac_f32_e32 v66, v74, v74
	v_add_f32_e32 v64, v64, v65
	v_add_f32_e32 v64, v64, v66
	v_fmac_f32_e32 v67, v72, v72
	v_add_f32_e32 v64, v67, v64
	v_add_f32_e32 v64, v82, v64
	ds_bpermute_b32 v65, v120, v64
	v_cvt_pk_bf16_f32 v66, v68, v69
	v_cvt_pk_bf16_f32 v67, v70, v71
	v_cvt_pk_bf16_f32 v68, v74, v75
	v_cvt_pk_bf16_f32 v69, v72, v73
	s_waitcnt lgkmcnt(0)
	v_add_f32_e32 v64, v64, v65
	ds_bpermute_b32 v65, v116, v64
	global_store_dwordx4 v[92:93], v[66:69], off offset:256
	s_and_saveexec_b64 s[22:23], s[2:3]
	s_cbranch_execz .LBB0_766
	v_lshl_add_u64 v[66:67], v[80:81], 2, s[8:9]
	s_waitcnt lgkmcnt(0)
	v_add_f32_e32 v64, v64, v65
	global_atomic_add_f32 v[66:67], v64, off

; __device__ __forceinline__ u32x4 pack8(f32x4 a, f32x4 b) { u32x4 w; w.x = cvt_pk_bf16(a[0], a[1]); w.y = cvt_pk_bf16(a[2], a[3]); w.z = cvt_pk_bf16(b[0], b[1]); w.w = cvt_pk_bf16(b[2], b[3]); return w; }
;     __device__ __forceinline__ void operator()(const f32x4 (&acc)[2][2][4][2], const pg8::Unit& u, int wr, int wc, int fr, int fq) const {
;     ...
;             for (int m = 0; m < 4; ++m) { const int row = u.pm * 256 + ai * 128 + wr * 64 + m * 16 + fr; float ss = 0.f;
;                 const float* xrow = row < MP ? xp + (size_t)row * D : xs + (size_t)(row - MP) * D;
; #pragma unroll
;                 for (int bj = 0; bj < 2; ++bj) { const int col = u.pn * 256 + bj * 128 + wc * 32 + 8 * fq;
;                     f32x4 v0 = acc[ai][bj][m][0] + *(const f32x4*)(xrow + col), v1 = acc[ai][bj][m][1] + *(const f32x4*)(xrow + col + 4);
;                     ss += (v0[0] * v0[0] + v0[1] * v0[1]) + (v0[2] * v0[2] + v0[3] * v0[3]) + (v1[0] * v1[0] + v1[1] * v1[1]) + (v1[2] * v1[2] + v1[3] * v1[3]);
;                     *(u32x4*)(X2B + (size_t)row * D + col) = pack8(v0, v1); }
.LBB0_793:
	s_waitcnt vmcnt(0)
	v_readlane_b32 s46, v254, 22
	s_barrier
	s_and_b32 s0, s44, 7
	s_lshr_b32 s1, s44, 3
	s_and_b32 s1, s1, 7
	s_lshl_b32 s0, s0, 3
	s_add_i32 s0, s0, s1
	s_mulk_i32 s0, 0x110
	s_addk_i32 s0, 0x100
	s_lshr_b32 s1, s44, 6
	v_readlane_b32 s2, v254, 21
	s_nop 3
	s_lshl_b32 s3, s1, 8
	s_lshl_b32 s2, s2, 5
	s_add_i32 s3, s3, s2
	s_mov_b32 s4, 0x800
	s_add_u32 s8, s88, 0x3000000
	s_addc_u32 s9, s89, 0
	s_add_u32 s10, s88, 0x1a00000
	s_addc_u32 s11, s89, 0
	s_mov_b64 s[6:7], 0x2000
	s_mov_b64 s[12:13], 0x200
	v_and_b32_e32 v8, 15, v132
	v_lshrrev_b32_e32 v9, 4, v132
	v_add_u32_e32 v5, s0, v8
	v_lshrrev_b32_e32 v6, 2, v8
	v_and_b32_e32 v7, 3, v8
	v_lshl_add_u32 v6, v6, 3, v7
	v_add_u32_e32 v6, s3, v6
	v_lshlrev_b32_e32 v7, 4, v9
	v_mul_lo_u32 v10, v5, s4
	v_mul_lo_u32 v12, v6, s4
	v_mov_b32_e32 v11, 0
	v_mov_b32_e32 v13, 0
	v_add_u32_e32 v10, v10, v7
	v_add_u32_e32 v12, v12, v7
	v_lshl_add_u64 v[10:11], s[8:9], 0, v[10:11]
	v_lshl_add_u64 v[12:13], s[10:11], 0, v[12:13]
	v_lshl_add_u64 v[14:15], v[12:13], 0, s[6:7]
	v_lshl_add_u32 v2, v9, 3, s3
	s_cmp_lt_u32 s0, 0x4000
	s_cselect_b32 s20, s52, s54
	s_cselect_b32 s21, s53, s55
	s_cselect_b32 s22, 0, 0x4000
	v_subrev_u32_e32 v0, s22, v5
	v_lshlrev_b32_e32 v0, 12, v0
	v_lshl_add_u32 v0, v2, 2, v0
	v_mov_b32_e32 v1, 0
	v_lshl_add_u64 v[0:1], s[20:21], 0, v[0:1]
	global_load_dwordx4 v[120:123], v[0:1], off
	global_load_dwordx4 v[124:127], v[0:1], off offset:16
	v_mov_b32_e32 v16, 0
	v_mov_b32_e32 v17, 0
	v_mov_b32_e32 v18, 0
	v_mov_b32_e32 v19, 0
	v_mov_b32_e32 v20, 0
	v_mov_b32_e32 v21, 0
	v_mov_b32_e32 v22, 0
	v_mov_b32_e32 v23, 0
	global_load_dwordx4 v[24:27], v[10:11], off
	global_load_dwordx4 v[28:31], v[12:13], off
	global_load_dwordx4 v[32:35], v[14:15], off
	global_load_dwordx4 v[36:39], v[10:11], off offset:64
	global_load_dwordx4 v[40:43], v[12:13], off offset:64
	global_load_dwordx4 v[44:47], v[14:15], off offset:64
	global_load_dwordx4 v[48:51], v[10:11], off offset:128
	global_load_dwordx4 v[52:55], v[12:13], off offset:128
	global_load_dwordx4 v[56:59], v[14:15], off offset:128
	global_load_dwordx4 v[60:63], v[10:11], off offset:192
	global_load_dwordx4 v[64:67], v[12:13], off offset:192
	global_load_dwordx4 v[68:71], v[14:15], off offset:192
	global_load_dwordx4 v[72:75], v[10:11], off offset:256
	global_load_dwordx4 v[76:79], v[12:13], off offset:256
	global_load_dwordx4 v[80:83], v[14:15], off offset:256
	global_load_dwordx4 v[84:87], v[10:11], off offset:320
	global_load_dwordx4 v[88:91], v[12:13], off offset:320
	global_load_dwordx4 v[92:95], v[14:15], off offset:320
	global_load_dwordx4 v[96:99], v[10:11], off offset:384
	global_load_dwordx4 v[100:103], v[12:13], off offset:384
	global_load_dwordx4 v[104:107], v[14:15], off offset:384
	global_load_dwordx4 v[108:111], v[10:11], off offset:448
	global_load_dwordx4 v[112:115], v[12:13], off offset:448
	global_load_dwordx4 v[116:119], v[14:15], off offset:448
	s_mov_b32 s5, 3
; __device__ __forceinline__ u32x4 pack8(f32x4 a, f32x4 b) { u32x4 w; w.x = cvt_pk_bf16(a[0], a[1]); w.y = cvt_pk_bf16(a[2], a[3]); w.z = cvt_pk_bf16(b[0], b[1]); w.w = cvt_pk_bf16(b[2], b[3]); return w; }
;     __device__ __forceinline__ void operator()(const f32x4 (&acc)[2][2][4][2], const pg8::Unit& u, int wr, int wc, int fr, int fq) const {
;     ...
;             for (int m = 0; m < 4; ++m) { const int row = u.pm * 256 + ai * 128 + wr * 64 + m * 16 + fr; float ss = 0.f;
;                 const float* xrow = row < MP ? xp + (size_t)row * D : xs + (size_t)(row - MP) * D;
; #pragma unroll
;                 for (int bj = 0; bj < 2; ++bj) { const int col = u.pn * 256 + bj * 128 + wc * 32 + 8 * fq;
;                     f32x4 v0 = acc[ai][bj][m][0] + *(const f32x4*)(xrow + col), v1 = acc[ai][bj][m][1] + *(const f32x4*)(xrow + col + 4);
;                     ss += (v0[0] * v0[0] + v0[1] * v0[1]) + (v0[2] * v0[2] + v0[3] * v0[3]) + (v1[0] * v1[0] + v1[1] * v1[1]) + (v1[2] * v1[2] + v1[3] * v1[3]);
;                     *(u32x4*)(X2B + (size_t)row * D + col) = pack8(v0, v1); }
;                 ss += __shfl_xor(ss, 16); ss += __shfl_xor(ss, 32);
;                 if (fq == 0) atomicAdd(rss + row, ss); }
.Lstrip_P4_k1:
	s_waitcnt vmcnt(21)
	v_mfma_f32_16x16x32_bf16 v[16:19], v[28:31], v[24:27], v[16:19]
	v_mfma_f32_16x16x32_bf16 v[20:23], v[32:35], v[24:27], v[20:23]
	global_load_dwordx4 v[24:27], v[10:11], off offset:512
	global_load_dwordx4 v[28:31], v[12:13], off offset:512
	global_load_dwordx4 v[32:35], v[14:15], off offset:512
	s_waitcnt vmcnt(21)
	v_mfma_f32_16x16x32_bf16 v[16:19], v[40:43], v[36:39], v[16:19]
	v_mfma_f32_16x16x32_bf16 v[20:23], v[44:47], v[36:39], v[20:23]
	global_load_dwordx4 v[36:39], v[10:11], off offset:576
	global_load_dwordx4 v[40:43], v[12:13], off offset:576
	global_load_dwordx4 v[44:47], v[14:15], off offset:576
	s_waitcnt vmcnt(21)
	v_mfma_f32_16x16x32_bf16 v[16:19], v[52:55], v[48:51], v[16:19]
	v_mfma_f32_16x16x32_bf16 v[20:23], v[56:59], v[48:51], v[20:23]
	global_load_dwordx4 v[48:51], v[10:11], off offset:640
	global_load_dwordx4 v[52:55], v[12:13], off offset:640
	global_load_dwordx4 v[56:59], v[14:15], off offset:640
	s_waitcnt vmcnt(21)
	v_mfma_f32_16x16x32_bf16 v[16:19], v[64:67], v[60:63], v[16:19]
	v_mfma_f32_16x16x32_bf16 v[20:23], v[68:71], v[60:63], v[20:23]
	global_load_dwordx4 v[60:63], v[10:11], off offset:704
	global_load_dwordx4 v[64:67], v[12:13], off offset:704
	global_load_dwordx4 v[68:71], v[14:15], off offset:704
	s_waitcnt vmcnt(21)
	v_mfma_f32_16x16x32_bf16 v[16:19], v[76:79], v[72:75], v[16:19]
	v_mfma_f32_16x16x32_bf16 v[20:23], v[80:83], v[72:75], v[20:23]
	global_load_dwordx4 v[72:75], v[10:11], off offset:768
	global_load_dwordx4 v[76:79], v[12:13], off offset:768
	global_load_dwordx4 v[80:83], v[14:15], off offset:768
	s_waitcnt vmcnt(21)
	v_mfma_f32_16x16x32_bf16 v[16:19], v[88:91], v[84:87], v[16:19]
	v_mfma_f32_16x16x32_bf16 v[20:23], v[92:95], v[84:87], v[20:23]
	global_load_dwordx4 v[84:87], v[10:11], off offset:832
	global_load_dwordx4 v[88:91], v[12:13], off offset:832
	global_load_dwordx4 v[92:95], v[14:15], off offset:832
	s_waitcnt vmcnt(21)
	v_mfma_f32_16x16x32_bf16 v[16:19], v[100:103], v[96:99], v[16:19]
	v_mfma_f32_16x16x32_bf16 v[20:23], v[104:107], v[96:99], v[20:23]
	global_load_dwordx4 v[96:99], v[10:11], off offset:896
	global_load_dwordx4 v[100:103], v[12:13], off offset:896
	global_load_dwordx4 v[104:107], v[14:15], off offset:896
	s_waitcnt vmcnt(21)
	v_mfma_f32_16x16x32_bf16 v[16:19], v[112:115], v[108:111], v[16:19]
	v_mfma_f32_16x16x32_bf16 v[20:23], v[116:119], v[108:111], v[20:23]
	global_load_dwordx4 v[108:111], v[10:11], off offset:960
	global_load_dwordx4 v[112:115], v[12:13], off offset:960
	global_load_dwordx4 v[116:119], v[14:15], off offset:960
	v_lshl_add_u64 v[10:11], v[10:11], 0, s[12:13]
	v_lshl_add_u64 v[12:13], v[12:13], 0, s[12:13]
	v_lshl_add_u64 v[14:15], v[14:15], 0, s[12:13]
	s_add_i32 s5, s5, -1
	s_cmp_lg_u32 s5, 0
	s_cbranch_scc1 .Lstrip_P4_k1
	s_waitcnt vmcnt(21)
	v_mfma_f32_16x16x32_bf16 v[16:19], v[28:31], v[24:27], v[16:19]
	v_mfma_f32_16x16x32_bf16 v[20:23], v[32:35], v[24:27], v[20:23]
	s_waitcnt vmcnt(18)
	v_mfma_f32_16x16x32_bf16 v[16:19], v[40:43], v[36:39], v[16:19]
	v_mfma_f32_16x16x32_bf16 v[20:23], v[44:47], v[36:39], v[20:23]
	s_waitcnt vmcnt(15)
	v_mfma_f32_16x16x32_bf16 v[16:19], v[52:55], v[48:51], v[16:19]
	v_mfma_f32_16x16x32_bf16 v[20:23], v[56:59], v[48:51], v[20:23]
	s_waitcnt vmcnt(12)
	v_mfma_f32_16x16x32_bf16 v[16:19], v[64:67], v[60:63], v[16:19]
	v_mfma_f32_16x16x32_bf16 v[20:23], v[68:71], v[60:63], v[20:23]
	s_waitcnt vmcnt(9)
	v_mfma_f32_16x16x32_bf16 v[16:19], v[76:79], v[72:75], v[16:19]
	v_mfma_f32_16x16x32_bf16 v[20:23], v[80:83], v[72:75], v[20:23]
	s_waitcnt vmcnt(6)
	v_mfma_f32_16x16x32_bf16 v[16:19], v[88:91], v[84:87], v[16:19]
	v_mfma_f32_16x16x32_bf16 v[20:23], v[92:95], v[84:87], v[20:23]
	s_waitcnt vmcnt(3)
	v_mfma_f32_16x16x32_bf16 v[16:19], v[100:103], v[96:99], v[16:19]
	v_mfma_f32_16x16x32_bf16 v[20:23], v[104:107], v[96:99], v[20:23]
	s_waitcnt vmcnt(0)
	v_mfma_f32_16x16x32_bf16 v[16:19], v[112:115], v[108:111], v[16:19]
	v_mfma_f32_16x16x32_bf16 v[20:23], v[116:119], v[108:111], v[20:23]
	s_nop 7
	s_nop 1
	v_add_f32_e32 v16, v16, v120
	v_add_f32_e32 v17, v17, v121
	v_add_f32_e32 v18, v18, v122
	v_add_f32_e32 v19, v19, v123
	v_add_f32_e32 v20, v20, v124
	v_add_f32_e32 v21, v21, v125
	v_add_f32_e32 v22, v22, v126
	v_add_f32_e32 v23, v23, v127
	v_mul_f32_e32 v144, v16, v16
	v_fmac_f32_e32 v144, v17, v17
	v_fmac_f32_e32 v144, v18, v18
	v_fmac_f32_e32 v144, v19, v19
	v_fmac_f32_e32 v144, v20, v20
	v_fmac_f32_e32 v144, v21, v21
	v_fmac_f32_e32 v144, v22, v22
	v_fmac_f32_e32 v144, v23, v23
	v_cvt_pk_bf16_f32 v136, v16, v17
	v_cvt_pk_bf16_f32 v137, v18, v19
	v_cvt_pk_bf16_f32 v138, v20, v21
	v_cvt_pk_bf16_f32 v139, v22, v23
	s_add_u32 s20, s88, 0x18400000
	s_addc_u32 s21, s89, 0
	v_lshlrev_b32_e32 v0, 11, v5
	v_lshl_add_u32 v0, v2, 1, v0
	v_mov_b32_e32 v1, 0
	v_lshl_add_u64 v[0:1], s[20:21], 0, v[0:1]
	global_store_dwordx4 v[0:1], v[136:139], off
	v_lshlrev_b32_e32 v146, 2, v132
	v_xor_b32_e32 v145, 64, v146
	v_xor_b32_e32 v146, 0x80, v146
	ds_bpermute_b32 v147, v145, v144
	s_add_u32 s20, s88, 0x100000
	s_addc_u32 s21, s89, 0
	v_lshlrev_b32_e32 v0, 2, v5
	v_mov_b32_e32 v1, 0
	v_lshl_add_u64 v[0:1], s[20:21], 0, v[0:1]
	v_cmp_gt_u32_e32 vcc, 16, v132
	s_waitcnt lgkmcnt(0)
	v_add_f32_e32 v144, v144, v147
	ds_bpermute_b32 v147, v146, v144
	s_waitcnt lgkmcnt(0)
	v_add_f32_e32 v144, v144, v147
	s_and_saveexec_b64 s[22:23], vcc
	global_atomic_add_f32 v[0:1], v144, off
	s_or_b64 exec, exec, s[22:23]

; #define LAS __attribute__((address_space(3)))
;     __device__ bool next(int i, Unit& u) const {
;         const long L = (long)i * G + c; if (L >= nwg) return false;
;         int wgid = (int)L; { const int q = nwg / NXCD, r = nwg % NXCD, xcd = wgid % NXCD, off = wgid / NXCD; wgid = (xcd < r ? xcd * (q + 1) : r * (q + 1) + (xcd - r) * q) + off; }
;         const int nig = WGM * nN, gid = wgid / nig, fm = gid * WGM, gsz = (nM - fm) < WGM ? (nM - fm) : WGM;
;         u.pm = fm + ((wgid % nig) % gsz); u.pn = (wgid % nig) / gsz; return true;
;     }
; __device__ __forceinline__ unsigned cvt_pk_bf16(float lo, float hi) { unsigned r; asm volatile("v_cvt_pk_bf16_f32 %0, %1, %2" : "=v"(r) : "v"(lo), "v"(hi)); return r; }
; template <class Epi>
; __device__ __forceinline__ void gemm_phase(LAS unsigned char* lds, const Gemm g, const StaticOrder& S, const Epi& E) {
;     const int tid = threadIdx.x, wid = __builtin_amdgcn_readfirstlane(tid >> 6), lane = tid & 63, wr = wid >> 2, wc = wid & 3, fr = lane & 15, fq = lane >> 4;
;     const int K = g.K, nt = K / BK;
;     unsigned voffA[2], voffB[2];
; #pragma unroll
;     for (int i = 0; i < 2; ++i) { int R, C; stage_rc(tid * 16 + i * 8192, R, C); const int Rb = (R & ~31) + perm32(R & 31);
;         voffA[i] = (unsigned)(R * K + C) * 2u; voffB[i] = (unsigned)(Rb * K + C) * 2u; }
;     const size_t kstep = (size_t)(BK * 2);
;     const size_t hstep = (size_t)HALF * K * 2;
;     const size_t tstep = 2 * hstep;
;     const unsigned ldsw = (unsigned)wid * 1024u;
;     const int aoff = lds_byte(wr * 64 + fr, fq * 8), boff = lds_byte(wc * 32 + fr, fq * 8);
;     ...
;     Unit cur, nxt; int ui = 0;
;     if (!S.next(0, cur)) return;
;     f32x4 acc[2][2][4][2];
; #pragma unroll
;     for (int a = 0; a < 2; ++a)
; #pragma unroll
;         for (int b = 0; b < 2; ++b)
; #pragma unroll
;             for (int m = 0; m < 4; ++m)
; #pragma unroll
;                 for (int n = 0; n < 2; ++n) acc[a][b][m][n] = (f32x4){0.f, 0.f, 0.f, 0.f};
;     bf16x8 At[4][2], B0[2][2], B1[2][2];
;     const char* cA = (const char*)g.A + (size_t)cur.pm * tstep; const char* cB = (const char*)g.Bt + (size_t)cur.pn * tstep;
;     PG8_STAGE(PG8_SB(0, 0), cB, voffB); PG8_STAGE(PG8_SB(0, 1), cB + hstep, voffB); PG8_STAGE(PG8_SA(0, 0), cA, voffA); PG8_STAGE(PG8_SA(0, 1), cA + hstep, voffA);
;     if (wr == 1) PG8_BAR;
;     PG8_WAIT_V(2); PG8_BAR;
.LBB0_915:
	s_or_b64 exec, exec, s[0:1]
	s_cmp_lt_i32 s90, 7
	s_cselect_b64 s[0:1], -1, 0
	s_cmp_gt_i32 s91, 6
	s_cselect_b64 s[2:3], -1, 0
	s_and_b64 s[0:1], s[0:1], s[2:3]
	s_andn2_b64 vcc, exec, s[0:1]
	s_waitcnt lgkmcnt(0)
	s_barrier
	s_cbranch_vccnz .LBB0_954
	s_cmpk_lt_i32 s44, 0x110
	s_cselect_b64 s[0:1], -1, 0
	s_cmpk_gt_i32 s44, 0x10f
	v_readfirstlane_b32 s2, v134
	s_cbranch_scc1 .LBB0_918
	s_ashr_i32 s3, s44, 31
	s_lshr_b32 s3, s3, 29
	s_add_i32 s3, s44, s3
	s_ashr_i32 s4, s3, 3
	s_and_b32 s3, s3, -8
	s_sub_i32 s3, s44, s3
	s_cmp_lt_i32 s3, 0
	s_cselect_b32 s5, 35, 34
	s_mul_i32 s3, s3, s5
	s_add_i32 s3, s3, s4
	s_ashr_i32 s4, s3, 31
	s_lshr_b32 s4, s4, 27
	s_add_i32 s4, s3, s4
	s_ashr_i32 s5, s4, 5
	s_lshl_b32 s6, s5, 3
	s_sub_i32 s5, 0x44, s6
	s_min_u32 s7, s5, 8
	s_andn2_b32 s4, s4, 31
	s_sub_i32 s3, s3, s4
	v_cvt_f32_ubyte0_e32 v1, s7
	v_cvt_f32_i32_e32 v0, s3
	v_rcp_iflag_f32_e32 v2, v1
	s_ashr_i32 s4, s3, 30
	s_or_b32 s8, s4, 1
	v_mul_f32_e32 v2, v0, v2
	v_trunc_f32_e32 v2, v2
	v_fma_f32 v0, -v2, v1, v0
	v_cvt_i32_f32_e32 v2, v2
	v_cmp_ge_f32_e64 s[4:5], |v0|, v1
	s_and_b64 s[4:5], s[4:5], exec
	s_cselect_b32 s4, s8, 0
	v_readfirstlane_b32 s5, v2
	s_add_i32 s4, s5, s4
	s_sext_i32_i8 s47, s4
	s_mul_i32 s4, s4, s7
	s_sub_i32 s3, s3, s4
	s_sext_i32_i8 s3, s3
	s_add_i32 s48, s6, s3
	s_and_b32 s3, s44, 7
	s_lshr_b32 s4, s44, 3
	s_and_b32 s4, s4, 7
	s_lshl_b32 s3, s3, 3
	s_add_i32 s3, s3, s4
	s_mul_i32 s48, s3, 17
	s_lshr_b32 s47, s44, 6
.LBB0_918:
	s_andn2_b64 vcc, exec, s[0:1]
	s_cbranch_vccnz .LBB0_954
	v_lshrrev_b32_e32 v3, 1, v134
	v_lshrrev_b32_e32 v4, 5, v134
	v_and_b32_e32 v3, 24, v3
	v_and_b32_e32 v4, 4, v4
	v_bfe_u32 v5, v134, 2, 2
	v_lshlrev_b32_e32 v0, 4, v134
	v_and_b32_e32 v1, 32, v134
	v_bfe_u32 v2, v134, 2, 4
	v_or3_b32 v3, v4, v5, v3
	v_lshrrev_b32_e32 v4, 3, v134
	s_movk_i32 s1, 0x70
	s_add_u32 s26, s88, 0xb800000
	v_bitop3_b32 v8, v0, v1, 48 bitop3:0x6c
	v_and_or_b32 v5, v4, s1, v2
	s_movk_i32 s1, 0x60
	v_add_u32_e32 v0, 0x2000, v0
	s_addc_u32 s27, s89, 0
	v_and_or_b32 v4, v4, s1, v3
	v_lshrrev_b32_e32 v0, 7, v0
	s_movk_i32 s1, 0xf0
	s_add_u32 s28, s88, 0x2700000
	v_and_or_b32 v2, v0, s1, v2
	s_movk_i32 s1, 0xe0
	s_addc_u32 s29, s89, 0
	v_and_b32_e32 v9, 64, v134
	v_and_or_b32 v0, v0, s1, v3
	s_lshr_b32 s1, s2, 6
	s_lshr_b32 s0, s2, 8
	v_or_b32_e32 v1, v8, v9
	s_lshl_b32 s30, s1, 10
	s_mul_i32 s5, s47, 0x160000
	v_lshrrev_b32_e32 v1, 1, v1
	v_mul_u32_u24_e32 v4, 0xb00, v4
	s_mul_hi_i32 s4, s47, 0x160000
	s_add_u32 s22, s28, s5
	v_or_b32_e32 v4, v4, v1
	s_addc_u32 s23, s29, s4
	s_add_i32 s31, s30, 0
	v_lshlrev_b32_e32 v130, 1, v4
	v_mul_u32_u24_e32 v0, 0xb00, v0
	s_add_i32 m0, s31, 0x10000
	v_or_b32_e32 v0, v0, v1
	global_load_lds_dwordx4 v130, s[22:23]
	s_add_i32 m0, s31, 0x12000
	v_lshlrev_b32_e32 v138, 1, v0
	s_add_u32 s4, s22, 0xb0000
	global_load_lds_dwordx4 v138, s[22:23]
	s_addc_u32 s5, s23, 0
	s_add_i32 m0, s31, 0x14000
	s_mul_i32 s6, s48, 0x16000
	global_load_lds_dwordx4 v130, s[4:5]
	s_add_i32 m0, s31, 0x16000
	v_mul_u32_u24_e32 v10, 0xb00, v5
	s_mul_hi_i32 s3, s48, 0x16000
	s_add_u32 s20, s26, s6
	v_or_b32_e32 v5, v1, v10
	v_mul_u32_u24_e32 v11, 0xb00, v2
	s_addc_u32 s21, s27, s3
	s_add_i32 s33, s31, 0x2000
	v_lshlrev_b32_e32 v128, 1, v5
	v_or_b32_e32 v2, v11, v1
	global_load_lds_dwordx4 v138, s[4:5]
	s_mov_b32 m0, s31
	s_add_u32 s4, s20, 0xb0000
	v_lshlrev_b32_e32 v136, 1, v2
	global_load_lds_dwordx4 v128, s[20:21]
	s_mov_b32 m0, s33
	s_addc_u32 s5, s21, 0
	s_add_i32 s34, s31, 0x4000
	global_load_lds_dwordx4 v136, s[20:21]
	s_mov_b32 m0, s34
	s_add_i32 s35, s31, 0x6000
	global_load_lds_dwordx4 v128, s[4:5]
	s_mov_b32 m0, s35
	v_mov_b32_e32 v131, 0
	global_load_lds_dwordx4 v136, s[4:5]
	v_mov_b32_e32 v139, v131
	v_mov_b32_e32 v129, v131
	v_mov_b32_e32 v137, v131
	s_cmp_eq_u32 s0, 1
	s_mov_b32 s36, 0
	v_lshl_add_u64 v[6:7], s[22:23], 0, v[130:131]
	v_lshl_add_u64 v[4:5], s[22:23], 0, v[138:139]
	v_lshl_add_u64 v[0:1], s[20:21], 0, v[128:129]
	s_cselect_b64 s[6:7], -1, 0
	s_cmp_lg_u32 s0, 1
	v_lshl_add_u64 v[2:3], s[20:21], 0, v[136:137]
	s_cbranch_scc1 .LBB0_921
	s_barrier
.LBB0_921:
	s_add_u32 s8, s88, 0x18400000
	s_addc_u32 s9, s89, 0
	s_add_u32 s10, s88, 0x9600000
	s_addc_u32 s11, s89, 0
	s_add_u32 s12, s88, 0x120000
	s_addc_u32 s13, s89, 0
	s_lshl_b32 s1, s1, 5
	s_mov_b64 s[14:15], 0x80
	s_and_b32 s1, s1, 0x60
	s_add_i32 m0, s31, 0x18000
	v_lshl_add_u64 v[6:7], v[6:7], 0, s[14:15]
	s_lshl_b32 s3, s0, 13
	s_lshl_b32 s16, s1, 7
	s_waitcnt vmcnt(2)
	s_barrier
	global_load_lds_dwordx4 v[6:7], off
	v_lshl_add_u64 v[4:5], v[4:5], 0, s[14:15]
	s_add_i32 m0, s31, 0x1a000
	s_add_i32 s37, s31, 0x8000
	s_add_i32 s38, s31, 0xa000
	global_load_lds_dwordx4 v[4:5], off
	v_lshl_add_u64 v[0:1], v[0:1], 0, s[14:15]
	s_mov_b32 m0, s37
	s_add_u32 s4, s22, 0xb0080
	global_load_lds_dwordx4 v[0:1], off
	v_lshl_add_u64 v[0:1], v[2:3], 0, s[14:15]
	s_mov_b32 m0, s38
	s_addc_u32 s5, s23, 0
	global_load_lds_dwordx4 v[0:1], off
	s_add_i32 m0, s31, 0x1c000
	v_lshl_add_u64 v[0:1], s[4:5], 0, v[130:131]
	global_load_lds_dwordx4 v[0:1], off
	v_lshl_add_u64 v[0:1], s[4:5], 0, v[138:139]
	s_add_i32 m0, s31, 0x1e000
	v_lshlrev_b32_e32 v3, 2, v134
	global_load_lds_dwordx4 v[0:1], off
	v_bfe_u32 v1, v134, 4, 2
	v_and_b32_e32 v0, 15, v134
	v_lshlrev_b32_e32 v2, 4, v1
	v_lshl_or_b32 v133, s0, 6, v0
	v_lshl_or_b32 v0, v0, 6, v2
	v_and_b32_e32 v3, 32, v3
	v_lshlrev_b32_e32 v4, 6, v134
	s_movk_i32 s0, 0x3c0
	v_bitop3_b32 v0, v0, s3, v3 bitop3:0xde
	v_and_or_b32 v2, v4, s0, v2
	s_waitcnt vmcnt(6)
	s_cmpk_lt_u32 s2, 0x100
	v_cmp_eq_u32_e64 s[2:3], 0, v1
	v_lshl_or_b32 v151, v1, 3, s1
	v_add_u16_e32 v1, v8, v9
	v_bitop3_b32 v150, s16, v2, v3 bitop3:0xf6
	s_cselect_b64 s[16:17], -1, 0
	v_lshrrev_b16_e32 v1, 1, v1
	s_add_i32 s42, 0, 0x10000
	s_add_i32 s43, 0, 0x14000
	v_add_u32_e32 v154, 0, v0
	v_mbcnt_lo_u32_b32 v0, -1, 0
	s_ashr_i32 s39, s94, 31
	s_mov_b32 s40, s94
	s_ashr_i32 s41, s44, 31
	v_add_lshl_u32 v134, v10, v1, 1
	v_mov_b32_e32 v135, v131
	v_add_lshl_u32 v140, v11, v1, 1
	v_mov_b32_e32 v141, v131
	v_mov_b64_e32 v[142:143], 0x100
	v_mov_b64_e32 v[144:145], 0xff
	v_add_u32_e32 v152, s42, v150
	v_add_u32_e32 v153, s43, v150
	v_mbcnt_hi_u32_b32 v155, -1, v0
	s_barrier
	s_branch .LBB0_924

; __device__ __forceinline__ u32x4 pack8(f32x4 a, f32x4 b) { u32x4 w; w.x = cvt_pk_bf16(a[0], a[1]); w.y = cvt_pk_bf16(a[2], a[3]); w.z = cvt_pk_bf16(b[0], b[1]); w.w = cvt_pk_bf16(b[2], b[3]); return w; }
;     __device__ __forceinline__ void operator()(const f32x4 (&acc)[2][2][4][2], const pg8::Unit& u, int wr, int wc, int fr, int fq) const {
; #pragma unroll
;         for (int ai = 0; ai < 2; ++ai)
; #pragma unroll
;             for (int m = 0; m < 4; ++m) { const int row = u.pm * 256 + ai * 128 + wr * 64 + m * 16 + fr; float ss = 0.f;
; #pragma unroll
;                 for (int bj = 0; bj < 2; ++bj) { const int col = u.pn * 256 + bj * 128 + wc * 32 + 8 * fq;
;                     f32x4 x0, x1; unpack_bf16x8(*(const u32x4*)(X2B + (size_t)row * D + col), x0, x1);
;                     const f32x4 v0 = acc[ai][bj][m][0] + x0, v1 = acc[ai][bj][m][1] + x1;
;                     ss += (v0[0] * v0[0] + v0[1] * v0[1]) + (v0[2] * v0[2] + v0[3] * v0[3]) + (v1[0] * v1[0] + v1[1] * v1[1]) + (v1[2] * v1[2] + v1[3] * v1[3]);
;                     *(u32x4*)(X3B + (size_t)row * D + col) = pack8(v0, v1); }
;                 ss += __shfl_xor(ss, 16); ss += __shfl_xor(ss, 32);
;                 if (fq == 0) atomicAdd(rss + row, ss); }
;     }
.LBB0_934:
	v_lshl_add_u32 v148, s48, 4, v133
	v_lshl_or_b32 v146, s47, 8, v151
	v_ashrrev_i32_e32 v149, 31, v148
	v_lshlrev_b64 v[160:161], 11, v[148:149]
	v_ashrrev_i32_e32 v147, 31, v146
	v_lshl_add_u64 v[156:157], s[8:9], 0, v[160:161]
	v_lshlrev_b64 v[146:147], 1, v[146:147]
	v_lshl_add_u64 v[162:163], v[156:157], 0, v[146:147]
	global_load_dwordx4 v[156:159], v[162:163], off
	s_waitcnt vmcnt(0)
	v_lshlrev_b32_e32 v164, 16, v156
	v_and_b32_e32 v165, 0xffff0000, v156
	v_lshlrev_b32_e32 v156, 16, v157
	v_and_b32_e32 v157, 0xffff0000, v157
	v_lshlrev_b32_e32 v166, 16, v158
	v_and_b32_e32 v167, 0xffff0000, v158
	v_lshlrev_b32_e32 v158, 16, v159
	v_and_b32_e32 v159, 0xffff0000, v159
	v_pk_add_f32 v[126:127], v[126:127], v[156:157]
	v_pk_add_f32 v[164:165], v[124:125], v[164:165]
	v_pk_add_f32 v[168:169], v[122:123], v[158:159]
	v_pk_add_f32 v[166:167], v[120:121], v[166:167]
	v_cvt_pk_bf16_f32 v122, v164, v165
	v_cvt_pk_bf16_f32 v123, v126, v127
	v_and_b32_e32 v121, 64, v155
	v_cvt_pk_bf16_f32 v124, v166, v167
	v_cvt_pk_bf16_f32 v125, v168, v169
	global_load_dwordx4 v[156:159], v[162:163], off offset:256
	v_xor_b32_e32 v120, 16, v155
	v_add_u32_e32 v121, 64, v121
	v_xor_b32_e32 v162, 32, v155
	v_cmp_lt_i32_e32 vcc, v120, v121
	v_mul_f32_e32 v127, v127, v127
	v_mul_f32_e32 v163, v167, v167
	v_cndmask_b32_e32 v120, v155, v120, vcc
	v_cmp_lt_i32_e32 vcc, v162, v121
	v_fmac_f32_e32 v127, v126, v126
	v_fmac_f32_e32 v163, v166, v166
	v_cndmask_b32_e32 v121, v155, v162, vcc
	v_mul_f32_e32 v162, v165, v165
	v_fmac_f32_e32 v162, v164, v164
	v_mul_f32_e32 v165, v169, v169
	v_add_f32_e32 v126, v162, v127
	v_fmac_f32_e32 v165, v168, v168
	v_add_f32_e32 v126, v163, v126
	v_add_f32_e32 v164, v165, v126
	v_lshlrev_b32_e32 v120, 2, v120
	s_waitcnt vmcnt(0)
	v_lshlrev_b32_e32 v126, 16, v156
	v_and_b32_e32 v127, 0xffff0000, v156
	v_lshlrev_b32_e32 v156, 16, v157
	v_and_b32_e32 v157, 0xffff0000, v157
	v_lshlrev_b32_e32 v162, 16, v158
	v_and_b32_e32 v163, 0xffff0000, v158
	v_pk_add_f32 v[118:119], v[118:119], v[156:157]
	v_pk_add_f32 v[116:117], v[116:117], v[126:127]
	v_lshlrev_b32_e32 v158, 16, v159
	v_and_b32_e32 v159, 0xffff0000, v159
	v_pk_add_f32 v[156:157], v[112:113], v[162:163]
	v_mul_f32_e32 v112, v117, v117
	v_mul_f32_e32 v113, v119, v119
	v_pk_add_f32 v[126:127], v[114:115], v[158:159]
	v_mul_f32_e32 v114, v157, v157
	v_fmac_f32_e32 v112, v116, v116
	v_fmac_f32_e32 v113, v118, v118
	v_mul_f32_e32 v115, v127, v127
	v_fmac_f32_e32 v114, v156, v156
	v_add_f32_e32 v112, v112, v113
	v_fmac_f32_e32 v115, v126, v126
	v_add_f32_e32 v112, v114, v112
	v_add_f32_e32 v112, v115, v112
	v_add_f32_e32 v114, v164, v112
	ds_bpermute_b32 v115, v120, v114
	v_lshl_add_u64 v[112:113], s[10:11], 0, v[160:161]
	v_lshl_add_u64 v[158:159], v[112:113], 0, v[146:147]
	global_store_dwordx4 v[158:159], v[122:125], off
	v_cvt_pk_bf16_f32 v116, v116, v117
	s_waitcnt lgkmcnt(0)
	v_add_f32_e32 v112, v114, v115
	v_lshlrev_b32_e32 v114, 2, v121
	ds_bpermute_b32 v113, v114, v112
	v_cvt_pk_bf16_f32 v117, v118, v119
	v_cvt_pk_bf16_f32 v118, v156, v157
	v_cvt_pk_bf16_f32 v119, v126, v127
	global_store_dwordx4 v[158:159], v[116:119], off offset:256
	s_and_saveexec_b64 s[20:21], s[2:3]
	s_cbranch_execz .LBB0_936
	v_lshl_add_u64 v[116:117], v[148:149], 2, s[12:13]
	s_waitcnt lgkmcnt(0)
	v_add_f32_e32 v112, v112, v113
	global_atomic_add_f32 v[116:117], v112, off
.LBB0_936:
	s_or_b64 exec, exec, s[20:21]
	v_add_u32_e32 v112, 16, v148
	s_waitcnt lgkmcnt(0)
	v_ashrrev_i32_e32 v113, 31, v112
	v_lshlrev_b64 v[122:123], 11, v[112:113]
	v_lshl_add_u64 v[116:117], s[8:9], 0, v[122:123]
	v_lshl_add_u64 v[124:125], v[116:117], 0, v[146:147]
	global_load_dwordx4 v[116:119], v[124:125], off
	s_waitcnt vmcnt(0)
	v_lshlrev_b32_e32 v126, 16, v116
	v_and_b32_e32 v127, 0xffff0000, v116
	v_lshlrev_b32_e32 v116, 16, v117
	v_and_b32_e32 v117, 0xffff0000, v117
	v_lshlrev_b32_e32 v156, 16, v118
	v_and_b32_e32 v157, 0xffff0000, v118
	v_lshlrev_b32_e32 v118, 16, v119
	v_and_b32_e32 v119, 0xffff0000, v119
	v_pk_add_f32 v[116:117], v[110:111], v[116:117]
	v_pk_add_f32 v[126:127], v[108:109], v[126:127]
	v_pk_add_f32 v[118:119], v[106:107], v[118:119]
	v_pk_add_f32 v[156:157], v[104:105], v[156:157]
	v_cvt_pk_bf16_f32 v104, v126, v127
	v_cvt_pk_bf16_f32 v105, v116, v117
	v_mul_f32_e32 v115, v127, v127
	v_cvt_pk_bf16_f32 v106, v156, v157
	v_cvt_pk_bf16_f32 v107, v118, v119
	global_load_dwordx4 v[108:111], v[124:125], off offset:256
	v_mul_f32_e32 v117, v117, v117
	v_mul_f32_e32 v121, v157, v157
	v_fmac_f32_e32 v115, v126, v126
	v_fmac_f32_e32 v117, v116, v116
	v_mul_f32_e32 v119, v119, v119
	v_fmac_f32_e32 v121, v156, v156
	v_add_f32_e32 v115, v115, v117
	v_fmac_f32_e32 v119, v118, v118
	v_add_f32_e32 v115, v121, v115
	v_add_f32_e32 v115, v119, v115
	s_waitcnt vmcnt(0)
	v_lshlrev_b32_e32 v116, 16, v108
	v_and_b32_e32 v117, 0xffff0000, v108
	v_lshlrev_b32_e32 v108, 16, v109
	v_and_b32_e32 v109, 0xffff0000, v109
	v_lshlrev_b32_e32 v118, 16, v110
	v_and_b32_e32 v119, 0xffff0000, v110
	v_lshlrev_b32_e32 v110, 16, v111
	v_and_b32_e32 v111, 0xffff0000, v111
	v_pk_add_f32 v[102:103], v[102:103], v[108:109]
	v_pk_add_f32 v[100:101], v[100:101], v[116:117]
	v_pk_add_f32 v[108:109], v[98:99], v[110:111]
	v_pk_add_f32 v[110:111], v[96:97], v[118:119]
	v_mul_f32_e32 v96, v101, v101
	v_mul_f32_e32 v97, v103, v103
	v_mul_f32_e32 v98, v111, v111
	v_fmac_f32_e32 v96, v100, v100
	v_fmac_f32_e32 v97, v102, v102
	v_mul_f32_e32 v99, v109, v109
	v_fmac_f32_e32 v98, v110, v110
	v_add_f32_e32 v96, v96, v97
	v_add_f32_e32 v96, v98, v96
	v_fmac_f32_e32 v99, v108, v108
	v_add_f32_e32 v96, v99, v96
	v_add_f32_e32 v99, v115, v96
	ds_bpermute_b32 v115, v120, v99
	v_lshl_add_u64 v[96:97], s[10:11], 0, v[122:123]
	v_lshl_add_u64 v[116:117], v[96:97], 0, v[146:147]
	global_store_dwordx4 v[116:117], v[104:107], off
	v_cvt_pk_bf16_f32 v98, v100, v101
	s_waitcnt lgkmcnt(0)
	v_add_f32_e32 v96, v99, v115
	ds_bpermute_b32 v97, v114, v96
	v_cvt_pk_bf16_f32 v99, v102, v103
	v_cvt_pk_bf16_f32 v100, v110, v111
	v_cvt_pk_bf16_f32 v101, v108, v109
	global_store_dwordx4 v[116:117], v[98:101], off offset:256
	s_and_saveexec_b64 s[20:21], s[2:3]
	s_cbranch_execz .LBB0_938
	v_lshl_add_u64 v[98:99], v[112:113], 2, s[12:13]
	s_waitcnt lgkmcnt(0)
	v_add_f32_e32 v96, v96, v97
	global_atomic_add_f32 v[98:99], v96, off
; __device__ __forceinline__ u32x4 pack8(f32x4 a, f32x4 b) { u32x4 w; w.x = cvt_pk_bf16(a[0], a[1]); w.y = cvt_pk_bf16(a[2], a[3]); w.z = cvt_pk_bf16(b[0], b[1]); w.w = cvt_pk_bf16(b[2], b[3]); return w; }
;     __device__ __forceinline__ void operator()(const f32x4 (&acc)[2][2][4][2], const pg8::Unit& u, int wr, int wc, int fr, int fq) const {
; #pragma unroll
;         for (int ai = 0; ai < 2; ++ai)
; #pragma unroll
;             for (int m = 0; m < 4; ++m) { const int row = u.pm * 256 + ai * 128 + wr * 64 + m * 16 + fr; float ss = 0.f;
; #pragma unroll
;                 for (int bj = 0; bj < 2; ++bj) { const int col = u.pn * 256 + bj * 128 + wc * 32 + 8 * fq;
;                     f32x4 x0, x1; unpack_bf16x8(*(const u32x4*)(X2B + (size_t)row * D + col), x0, x1);
;                     const f32x4 v0 = acc[ai][bj][m][0] + x0, v1 = acc[ai][bj][m][1] + x1;
;                     ss += (v0[0] * v0[0] + v0[1] * v0[1]) + (v0[2] * v0[2] + v0[3] * v0[3]) + (v1[0] * v1[0] + v1[1] * v1[1]) + (v1[2] * v1[2] + v1[3] * v1[3]);
;                     *(u32x4*)(X3B + (size_t)row * D + col) = pack8(v0, v1); }
;                 ss += __shfl_xor(ss, 16); ss += __shfl_xor(ss, 32);
;                 if (fq == 0) atomicAdd(rss + row, ss); }
;     }
.LBB0_938:
	s_or_b64 exec, exec, s[20:21]
	v_add_u32_e32 v96, 32, v148
	s_waitcnt lgkmcnt(0)
	v_ashrrev_i32_e32 v97, 31, v96
	v_lshlrev_b64 v[102:103], 11, v[96:97]
	v_lshl_add_u64 v[98:99], s[8:9], 0, v[102:103]
	v_lshl_add_u64 v[104:105], v[98:99], 0, v[146:147]
	global_load_dwordx4 v[98:101], v[104:105], off
	s_waitcnt vmcnt(0)
	v_lshlrev_b32_e32 v106, 16, v98
	v_and_b32_e32 v107, 0xffff0000, v98
	v_lshlrev_b32_e32 v98, 16, v99
	v_and_b32_e32 v99, 0xffff0000, v99
	v_lshlrev_b32_e32 v108, 16, v100
	v_and_b32_e32 v109, 0xffff0000, v100
	v_lshlrev_b32_e32 v100, 16, v101
	v_and_b32_e32 v101, 0xffff0000, v101
	v_pk_add_f32 v[98:99], v[94:95], v[98:99]
	v_pk_add_f32 v[106:107], v[92:93], v[106:107]
	v_pk_add_f32 v[100:101], v[90:91], v[100:101]
	v_pk_add_f32 v[108:109], v[88:89], v[108:109]
	v_cvt_pk_bf16_f32 v88, v106, v107
	v_cvt_pk_bf16_f32 v89, v98, v99
	v_mul_f32_e32 v99, v99, v99
	v_cvt_pk_bf16_f32 v90, v108, v109
	v_cvt_pk_bf16_f32 v91, v100, v101
	global_load_dwordx4 v[92:95], v[104:105], off offset:256
	v_mul_f32_e32 v104, v107, v107
	v_mul_f32_e32 v105, v109, v109
	v_fmac_f32_e32 v104, v106, v106
	v_fmac_f32_e32 v99, v98, v98
	v_mul_f32_e32 v101, v101, v101
	v_fmac_f32_e32 v105, v108, v108
	v_add_f32_e32 v98, v104, v99
	v_fmac_f32_e32 v101, v100, v100
	v_add_f32_e32 v98, v105, v98
	v_add_f32_e32 v104, v101, v98
	s_waitcnt vmcnt(0)
	v_lshlrev_b32_e32 v98, 16, v92
	v_and_b32_e32 v99, 0xffff0000, v92
	v_lshlrev_b32_e32 v92, 16, v93
	v_and_b32_e32 v93, 0xffff0000, v93
	v_lshlrev_b32_e32 v100, 16, v94
	v_and_b32_e32 v101, 0xffff0000, v94
	v_lshlrev_b32_e32 v94, 16, v95
	v_and_b32_e32 v95, 0xffff0000, v95
	v_pk_add_f32 v[86:87], v[86:87], v[92:93]
	v_pk_add_f32 v[84:85], v[84:85], v[98:99]
	v_pk_add_f32 v[92:93], v[82:83], v[94:95]
	v_pk_add_f32 v[94:95], v[80:81], v[100:101]
	v_mul_f32_e32 v80, v85, v85
	v_mul_f32_e32 v81, v87, v87
	v_mul_f32_e32 v82, v95, v95
	v_fmac_f32_e32 v80, v84, v84
	v_fmac_f32_e32 v81, v86, v86
	v_mul_f32_e32 v83, v93, v93
	v_fmac_f32_e32 v82, v94, v94
	v_add_f32_e32 v80, v80, v81
	v_add_f32_e32 v80, v82, v80
	v_fmac_f32_e32 v83, v92, v92
	v_add_f32_e32 v80, v83, v80
	v_add_f32_e32 v83, v104, v80
	ds_bpermute_b32 v100, v120, v83
	v_lshl_add_u64 v[80:81], s[10:11], 0, v[102:103]
	v_lshl_add_u64 v[98:99], v[80:81], 0, v[146:147]
	global_store_dwordx4 v[98:99], v[88:91], off
	v_cvt_pk_bf16_f32 v82, v84, v85
	s_waitcnt lgkmcnt(0)
	v_add_f32_e32 v80, v83, v100
	ds_bpermute_b32 v81, v114, v80
	v_cvt_pk_bf16_f32 v83, v86, v87
	v_cvt_pk_bf16_f32 v84, v94, v95
	v_cvt_pk_bf16_f32 v85, v92, v93
	global_store_dwordx4 v[98:99], v[82:85], off offset:256
	s_and_saveexec_b64 s[20:21], s[2:3]
	s_cbranch_execz .LBB0_940
	v_lshl_add_u64 v[82:83], v[96:97], 2, s[12:13]
	s_waitcnt lgkmcnt(0)
	v_add_f32_e32 v80, v80, v81
	global_atomic_add_f32 v[82:83], v80, off
.LBB0_940:
	s_or_b64 exec, exec, s[20:21]
	v_add_u32_e32 v80, 48, v148
	s_waitcnt lgkmcnt(0)
	v_ashrrev_i32_e32 v81, 31, v80
	v_lshlrev_b64 v[86:87], 11, v[80:81]
	v_lshl_add_u64 v[82:83], s[8:9], 0, v[86:87]
	v_lshl_add_u64 v[88:89], v[82:83], 0, v[146:147]
	global_load_dwordx4 v[82:85], v[88:89], off
	s_waitcnt vmcnt(0)
	v_lshlrev_b32_e32 v90, 16, v82
	v_and_b32_e32 v91, 0xffff0000, v82
	v_lshlrev_b32_e32 v82, 16, v83
	v_and_b32_e32 v83, 0xffff0000, v83
	v_lshlrev_b32_e32 v92, 16, v84
	v_and_b32_e32 v93, 0xffff0000, v84
	v_lshlrev_b32_e32 v84, 16, v85
	v_and_b32_e32 v85, 0xffff0000, v85
	v_pk_add_f32 v[82:83], v[78:79], v[82:83]
	v_pk_add_f32 v[90:91], v[76:77], v[90:91]
	v_pk_add_f32 v[84:85], v[74:75], v[84:85]
	v_pk_add_f32 v[92:93], v[72:73], v[92:93]
	v_cvt_pk_bf16_f32 v72, v90, v91
	v_cvt_pk_bf16_f32 v73, v82, v83
	v_mul_f32_e32 v83, v83, v83
	v_cvt_pk_bf16_f32 v74, v92, v93
	v_cvt_pk_bf16_f32 v75, v84, v85
	global_load_dwordx4 v[76:79], v[88:89], off offset:256
	v_mul_f32_e32 v88, v91, v91
	v_mul_f32_e32 v89, v93, v93
	v_fmac_f32_e32 v88, v90, v90
	v_fmac_f32_e32 v83, v82, v82
	v_mul_f32_e32 v85, v85, v85
	v_fmac_f32_e32 v89, v92, v92
	v_add_f32_e32 v82, v88, v83
	v_fmac_f32_e32 v85, v84, v84
	v_add_f32_e32 v82, v89, v82
	v_add_f32_e32 v88, v85, v82
	s_waitcnt vmcnt(0)
	v_lshlrev_b32_e32 v82, 16, v76
	v_and_b32_e32 v83, 0xffff0000, v76
	v_lshlrev_b32_e32 v76, 16, v77
	v_and_b32_e32 v77, 0xffff0000, v77
	v_lshlrev_b32_e32 v84, 16, v78
	v_and_b32_e32 v85, 0xffff0000, v78
	v_lshlrev_b32_e32 v78, 16, v79
	v_and_b32_e32 v79, 0xffff0000, v79
	v_pk_add_f32 v[70:71], v[70:71], v[76:77]
	v_pk_add_f32 v[68:69], v[68:69], v[82:83]
	v_pk_add_f32 v[76:77], v[66:67], v[78:79]
	v_pk_add_f32 v[78:79], v[64:65], v[84:85]
	v_mul_f32_e32 v64, v69, v69
	v_mul_f32_e32 v65, v71, v71
	v_mul_f32_e32 v66, v79, v79
	v_fmac_f32_e32 v64, v68, v68
	v_fmac_f32_e32 v65, v70, v70
	v_mul_f32_e32 v67, v77, v77
	v_fmac_f32_e32 v66, v78, v78
	v_add_f32_e32 v64, v64, v65
	v_add_f32_e32 v64, v66, v64
	v_fmac_f32_e32 v67, v76, v76
	v_add_f32_e32 v64, v67, v64
	v_add_f32_e32 v67, v88, v64
	ds_bpermute_b32 v84, v120, v67
	v_lshl_add_u64 v[64:65], s[10:11], 0, v[86:87]
	v_lshl_add_u64 v[82:83], v[64:65], 0, v[146:147]
	global_store_dwordx4 v[82:83], v[72:75], off
	v_cvt_pk_bf16_f32 v66, v68, v69
	s_waitcnt lgkmcnt(0)
	v_add_f32_e32 v64, v67, v84
	ds_bpermute_b32 v65, v114, v64
	v_cvt_pk_bf16_f32 v67, v70, v71
	v_cvt_pk_bf16_f32 v68, v78, v79
	v_cvt_pk_bf16_f32 v69, v76, v77
	global_store_dwordx4 v[82:83], v[66:69], off offset:256
	s_and_saveexec_b64 s[20:21], s[2:3]
	s_cbranch_execz .LBB0_942
	v_lshl_add_u64 v[66:67], v[80:81], 2, s[12:13]
	s_waitcnt lgkmcnt(0)
	v_add_f32_e32 v64, v64, v65
	global_atomic_add_f32 v[66:67], v64, off

;     __device__ __forceinline__ void operator()(const f32x4 (&acc)[2][2][4][2], const pg8::Unit& u, int wr, int wc, int fr, int fq) const {
;     ...
;             for (int m = 0; m < 4; ++m) { const int row = u.pm * 256 + ai * 128 + wr * 64 + m * 16 + fr; float ss = 0.f;
; #pragma unroll
;                 for (int bj = 0; bj < 2; ++bj) { const int col = u.pn * 256 + bj * 128 + wc * 32 + 8 * fq;
;                     f32x4 x0, x1; unpack_bf16x8(*(const u32x4*)(X2B + (size_t)row * D + col), x0, x1);
;                     const f32x4 v0 = acc[ai][bj][m][0] + x0, v1 = acc[ai][bj][m][1] + x1;
.LBB0_953:
	s_waitcnt vmcnt(0)
	v_readlane_b32 s46, v254, 22
	s_barrier
	s_and_b32 s0, s44, 7
	s_lshr_b32 s1, s44, 3
	s_and_b32 s1, s1, 7
	s_lshl_b32 s0, s0, 3
	s_add_i32 s0, s0, s1
	s_mulk_i32 s0, 0x110
	s_addk_i32 s0, 0x100
	s_lshr_b32 s1, s44, 6
	v_readlane_b32 s2, v254, 21
	s_nop 3
	s_lshl_b32 s3, s1, 8
	s_lshl_b32 s2, s2, 5
	s_add_i32 s3, s3, s2
	s_mov_b32 s4, 0x1600
	s_add_u32 s8, s88, 0xb800000
	s_addc_u32 s9, s89, 0
	s_add_u32 s10, s88, 0x2700000
	s_addc_u32 s11, s89, 0
	s_mov_b64 s[6:7], 0x5800
	s_mov_b64 s[12:13], 0x200
	v_and_b32_e32 v8, 15, v132
	v_lshrrev_b32_e32 v9, 4, v132
	v_add_u32_e32 v5, s0, v8
	v_lshrrev_b32_e32 v6, 2, v8
	v_and_b32_e32 v7, 3, v8
	v_lshl_add_u32 v6, v6, 3, v7
	v_add_u32_e32 v6, s3, v6
	v_lshlrev_b32_e32 v7, 4, v9
	v_mul_lo_u32 v10, v5, s4
	v_mul_lo_u32 v12, v6, s4
	v_mov_b32_e32 v11, 0
	v_mov_b32_e32 v13, 0
	v_add_u32_e32 v10, v10, v7
	v_add_u32_e32 v12, v12, v7
	v_lshl_add_u64 v[10:11], s[8:9], 0, v[10:11]
	v_lshl_add_u64 v[12:13], s[10:11], 0, v[12:13]
	v_lshl_add_u64 v[14:15], v[12:13], 0, s[6:7]
	v_lshl_add_u32 v2, v9, 3, s3
	s_add_u32 s20, s88, 0x18400000
	s_addc_u32 s21, s89, 0
	v_lshlrev_b32_e32 v0, 11, v5
	v_lshl_add_u32 v0, v2, 1, v0
	v_mov_b32_e32 v1, 0
	v_lshl_add_u64 v[0:1], s[20:21], 0, v[0:1]
	global_load_dwordx4 v[120:123], v[0:1], off
	v_mov_b32_e32 v16, 0
	v_mov_b32_e32 v17, 0
	v_mov_b32_e32 v18, 0
	v_mov_b32_e32 v19, 0
	v_mov_b32_e32 v20, 0
	v_mov_b32_e32 v21, 0
	v_mov_b32_e32 v22, 0
	v_mov_b32_e32 v23, 0
	global_load_dwordx4 v[24:27], v[10:11], off
	global_load_dwordx4 v[28:31], v[12:13], off
	global_load_dwordx4 v[32:35], v[14:15], off
	global_load_dwordx4 v[36:39], v[10:11], off offset:64
	global_load_dwordx4 v[40:43], v[12:13], off offset:64
	global_load_dwordx4 v[44:47], v[14:15], off offset:64
	global_load_dwordx4 v[48:51], v[10:11], off offset:128
	global_load_dwordx4 v[52:55], v[12:13], off offset:128
	global_load_dwordx4 v[56:59], v[14:15], off offset:128
	global_load_dwordx4 v[60:63], v[10:11], off offset:192
	global_load_dwordx4 v[64:67], v[12:13], off offset:192
	global_load_dwordx4 v[68:71], v[14:15], off offset:192
	global_load_dwordx4 v[72:75], v[10:11], off offset:256
	global_load_dwordx4 v[76:79], v[12:13], off offset:256
	global_load_dwordx4 v[80:83], v[14:15], off offset:256
	global_load_dwordx4 v[84:87], v[10:11], off offset:320
	global_load_dwordx4 v[88:91], v[12:13], off offset:320
	global_load_dwordx4 v[92:95], v[14:15], off offset:320
	global_load_dwordx4 v[96:99], v[10:11], off offset:384
	global_load_dwordx4 v[100:103], v[12:13], off offset:384
	global_load_dwordx4 v[104:107], v[14:15], off offset:384
	global_load_dwordx4 v[108:111], v[10:11], off offset:448
	global_load_dwordx4 v[112:115], v[12:13], off offset:448
	global_load_dwordx4 v[116:119], v[14:15], off offset:448
	s_mov_b32 s5, 10
; __device__ __forceinline__ u32x4 pack8(f32x4 a, f32x4 b) { u32x4 w; w.x = cvt_pk_bf16(a[0], a[1]); w.y = cvt_pk_bf16(a[2], a[3]); w.z = cvt_pk_bf16(b[0], b[1]); w.w = cvt_pk_bf16(b[2], b[3]); return w; }
;     __device__ __forceinline__ void operator()(const f32x4 (&acc)[2][2][4][2], const pg8::Unit& u, int wr, int wc, int fr, int fq) const {
;     ...
;             for (int m = 0; m < 4; ++m) { const int row = u.pm * 256 + ai * 128 + wr * 64 + m * 16 + fr; float ss = 0.f;
; #pragma unroll
;                 for (int bj = 0; bj < 2; ++bj) { const int col = u.pn * 256 + bj * 128 + wc * 32 + 8 * fq;
;                     f32x4 x0, x1; unpack_bf16x8(*(const u32x4*)(X2B + (size_t)row * D + col), x0, x1);
;                     const f32x4 v0 = acc[ai][bj][m][0] + x0, v1 = acc[ai][bj][m][1] + x1;
;                     ss += (v0[0] * v0[0] + v0[1] * v0[1]) + (v0[2] * v0[2] + v0[3] * v0[3]) + (v1[0] * v1[0] + v1[1] * v1[1]) + (v1[2] * v1[2] + v1[3] * v1[3]);
;                     *(u32x4*)(X3B + (size_t)row * D + col) = pack8(v0, v1); }
;                 ss += __shfl_xor(ss, 16); ss += __shfl_xor(ss, 32);
;                 if (fq == 0) atomicAdd(rss + row, ss); }
.Lstrip_P6_k1:
	s_waitcnt vmcnt(21)
	v_mfma_f32_16x16x32_bf16 v[16:19], v[28:31], v[24:27], v[16:19]
	v_mfma_f32_16x16x32_bf16 v[20:23], v[32:35], v[24:27], v[20:23]
	global_load_dwordx4 v[24:27], v[10:11], off offset:512
	global_load_dwordx4 v[28:31], v[12:13], off offset:512
	global_load_dwordx4 v[32:35], v[14:15], off offset:512
	s_waitcnt vmcnt(21)
	v_mfma_f32_16x16x32_bf16 v[16:19], v[40:43], v[36:39], v[16:19]
	v_mfma_f32_16x16x32_bf16 v[20:23], v[44:47], v[36:39], v[20:23]
	global_load_dwordx4 v[36:39], v[10:11], off offset:576
	global_load_dwordx4 v[40:43], v[12:13], off offset:576
	global_load_dwordx4 v[44:47], v[14:15], off offset:576
	s_waitcnt vmcnt(21)
	v_mfma_f32_16x16x32_bf16 v[16:19], v[52:55], v[48:51], v[16:19]
	v_mfma_f32_16x16x32_bf16 v[20:23], v[56:59], v[48:51], v[20:23]
	global_load_dwordx4 v[48:51], v[10:11], off offset:640
	global_load_dwordx4 v[52:55], v[12:13], off offset:640
	global_load_dwordx4 v[56:59], v[14:15], off offset:640
	s_waitcnt vmcnt(21)
	v_mfma_f32_16x16x32_bf16 v[16:19], v[64:67], v[60:63], v[16:19]
	v_mfma_f32_16x16x32_bf16 v[20:23], v[68:71], v[60:63], v[20:23]
	global_load_dwordx4 v[60:63], v[10:11], off offset:704
	global_load_dwordx4 v[64:67], v[12:13], off offset:704
	global_load_dwordx4 v[68:71], v[14:15], off offset:704
	s_waitcnt vmcnt(21)
	v_mfma_f32_16x16x32_bf16 v[16:19], v[76:79], v[72:75], v[16:19]
	v_mfma_f32_16x16x32_bf16 v[20:23], v[80:83], v[72:75], v[20:23]
	global_load_dwordx4 v[72:75], v[10:11], off offset:768
	global_load_dwordx4 v[76:79], v[12:13], off offset:768
	global_load_dwordx4 v[80:83], v[14:15], off offset:768
	s_waitcnt vmcnt(21)
	v_mfma_f32_16x16x32_bf16 v[16:19], v[88:91], v[84:87], v[16:19]
	v_mfma_f32_16x16x32_bf16 v[20:23], v[92:95], v[84:87], v[20:23]
	global_load_dwordx4 v[84:87], v[10:11], off offset:832
	global_load_dwordx4 v[88:91], v[12:13], off offset:832
	global_load_dwordx4 v[92:95], v[14:15], off offset:832
	s_waitcnt vmcnt(21)
	v_mfma_f32_16x16x32_bf16 v[16:19], v[100:103], v[96:99], v[16:19]
	v_mfma_f32_16x16x32_bf16 v[20:23], v[104:107], v[96:99], v[20:23]
	global_load_dwordx4 v[96:99], v[10:11], off offset:896
	global_load_dwordx4 v[100:103], v[12:13], off offset:896
	global_load_dwordx4 v[104:107], v[14:15], off offset:896
	s_waitcnt vmcnt(21)
	v_mfma_f32_16x16x32_bf16 v[16:19], v[112:115], v[108:111], v[16:19]
	v_mfma_f32_16x16x32_bf16 v[20:23], v[116:119], v[108:111], v[20:23]
	global_load_dwordx4 v[108:111], v[10:11], off offset:960
	global_load_dwordx4 v[112:115], v[12:13], off offset:960
	global_load_dwordx4 v[116:119], v[14:15], off offset:960
	v_lshl_add_u64 v[10:11], v[10:11], 0, s[12:13]
	v_lshl_add_u64 v[12:13], v[12:13], 0, s[12:13]
	v_lshl_add_u64 v[14:15], v[14:15], 0, s[12:13]
	s_add_i32 s5, s5, -1
	s_cmp_lg_u32 s5, 0
	s_cbranch_scc1 .Lstrip_P6_k1
	s_waitcnt vmcnt(21)
	v_mfma_f32_16x16x32_bf16 v[16:19], v[28:31], v[24:27], v[16:19]
	v_mfma_f32_16x16x32_bf16 v[20:23], v[32:35], v[24:27], v[20:23]
	s_waitcnt vmcnt(18)
	v_mfma_f32_16x16x32_bf16 v[16:19], v[40:43], v[36:39], v[16:19]
	v_mfma_f32_16x16x32_bf16 v[20:23], v[44:47], v[36:39], v[20:23]
	s_waitcnt vmcnt(15)
	v_mfma_f32_16x16x32_bf16 v[16:19], v[52:55], v[48:51], v[16:19]
	v_mfma_f32_16x16x32_bf16 v[20:23], v[56:59], v[48:51], v[20:23]
	s_waitcnt vmcnt(12)
	v_mfma_f32_16x16x32_bf16 v[16:19], v[64:67], v[60:63], v[16:19]
	v_mfma_f32_16x16x32_bf16 v[20:23], v[68:71], v[60:63], v[20:23]
	s_waitcnt vmcnt(9)
	v_mfma_f32_16x16x32_bf16 v[16:19], v[76:79], v[72:75], v[16:19]
	v_mfma_f32_16x16x32_bf16 v[20:23], v[80:83], v[72:75], v[20:23]
	s_waitcnt vmcnt(6)
	v_mfma_f32_16x16x32_bf16 v[16:19], v[88:91], v[84:87], v[16:19]
	v_mfma_f32_16x16x32_bf16 v[20:23], v[92:95], v[84:87], v[20:23]
	s_waitcnt vmcnt(3)
	v_mfma_f32_16x16x32_bf16 v[16:19], v[100:103], v[96:99], v[16:19]
	v_mfma_f32_16x16x32_bf16 v[20:23], v[104:107], v[96:99], v[20:23]
	s_waitcnt vmcnt(0)
	v_mfma_f32_16x16x32_bf16 v[16:19], v[112:115], v[108:111], v[16:19]
	v_mfma_f32_16x16x32_bf16 v[20:23], v[116:119], v[108:111], v[20:23]
	s_nop 7
	s_nop 1
	v_lshlrev_b32_e32 v136, 16, v120
	v_and_b32_e32 v137, 0xffff0000, v120
	v_lshlrev_b32_e32 v138, 16, v121
	v_and_b32_e32 v139, 0xffff0000, v121
	v_lshlrev_b32_e32 v140, 16, v122
	v_and_b32_e32 v141, 0xffff0000, v122
	v_lshlrev_b32_e32 v142, 16, v123
	v_and_b32_e32 v143, 0xffff0000, v123
	v_add_f32_e32 v16, v16, v136
	v_add_f32_e32 v17, v17, v137
	v_add_f32_e32 v18, v18, v138
	v_add_f32_e32 v19, v19, v139
	v_add_f32_e32 v20, v20, v140
	v_add_f32_e32 v21, v21, v141
	v_add_f32_e32 v22, v22, v142
	v_add_f32_e32 v23, v23, v143
	v_mul_f32_e32 v144, v16, v16
	v_fmac_f32_e32 v144, v17, v17
	v_fmac_f32_e32 v144, v18, v18
	v_fmac_f32_e32 v144, v19, v19
	v_fmac_f32_e32 v144, v20, v20
	v_fmac_f32_e32 v144, v21, v21
	v_fmac_f32_e32 v144, v22, v22
	v_fmac_f32_e32 v144, v23, v23
	v_cvt_pk_bf16_f32 v136, v16, v17
	v_cvt_pk_bf16_f32 v137, v18, v19
	v_cvt_pk_bf16_f32 v138, v20, v21
	v_cvt_pk_bf16_f32 v139, v22, v23
	s_add_u32 s20, s88, 0x9600000
	s_addc_u32 s21, s89, 0
	v_lshlrev_b32_e32 v0, 11, v5
	v_lshl_add_u32 v0, v2, 1, v0
	v_mov_b32_e32 v1, 0
	v_lshl_add_u64 v[0:1], s[20:21], 0, v[0:1]
	global_store_dwordx4 v[0:1], v[136:139], off
	v_lshlrev_b32_e32 v146, 2, v132
	v_xor_b32_e32 v145, 64, v146
	v_xor_b32_e32 v146, 0x80, v146
	ds_bpermute_b32 v147, v145, v144
	s_add_u32 s20, s88, 0x120000
	s_addc_u32 s21, s89, 0
	v_lshlrev_b32_e32 v0, 2, v5
	v_mov_b32_e32 v1, 0
	v_lshl_add_u64 v[0:1], s[20:21], 0, v[0:1]
	v_cmp_gt_u32_e32 vcc, 16, v132
	s_waitcnt lgkmcnt(0)
	v_add_f32_e32 v144, v144, v147
	ds_bpermute_b32 v147, v146, v144
	s_waitcnt lgkmcnt(0)
	v_add_f32_e32 v144, v144, v147
	s_and_saveexec_b64 s[22:23], vcc
	global_atomic_add_f32 v[0:1], v144, off
	s_or_b64 exec, exec, s[22:23]
